# DA main loop: keys permuted within each 16-key group so transposed V reads and K reads are bank-conflict-free; NSA steps: accumulator bias splat with v_mov_b64, row-sum chain starts without 0+x
# speedup vs baseline: 1.0034x; 1.0034x over previous
; #define LAS __attribute__((address_space(3)))
; DI float bf2f(unsigned short u) { return __uint_as_float(((unsigned)u) << 16); }
; #define NS_GLOAD(k_, KR, VR) do { const int jj = __builtin_amdgcn_readfirstlane(jl[(k_)]); KR = *(const u32x4*)(kg + (size_t)(64 * jj + sr) * pitch + sc * 8); VR = *(const u32x4*)(vg + (size_t)(64 * jj + sr) * pitch + sc * 8); } while (0)
; template <int MODE>
; DI void nsa_branch(lds8* lds, const bf16_t* kg, const bf16_t* vg, int pitch, unsigned tiles, const bf16x8 (&q)[4], int qpos, unsigned mybits, int blk,
;                    f32x16 (&O)[2], float& muse, float& l, int tid, int lane, int grp, CmpCap& cap) {
;   const int r = lane & 31, h = lane >> 5;
;   const int sr = tid >> 3, sc = tid & 7;
;   const int koff = r * NS_STR + h * 16;
;   const int voff = 64 * NS_STR + (4 * h + ((lane & 15) >> 2)) * NS_STR + ((lane >> 4) & 1) * 32 + (lane & 3) * 8;
;   volatile LAS int* jl = (volatile LAS int*)(lds + NS_LIST);
;   tiles = __builtin_amdgcn_readfirstlane(tiles);
;   const int ntl = __builtin_popcount(tiles);
;   if (tid < 32) { unsigned below = tiles & ((1u << tid) - 1u); if ((tiles >> tid) & 1u) jl[__builtin_popcount(below)] = tid; }
;   __syncthreads();
; #pragma unroll
;   for (int d = 0; d < 2; ++d)
; #pragma unroll
;     for (int i = 0; i < 16; ++i) O[d][i] = 0.f;
;   muse = 0.f; l = 0.f;
;   u32x4 kra, vra;
;     ...
;   NS_GLOAD(0, kra, vra); NS_LSTORE(0, kra, vra);
;   if (ntl > 1) { NS_GLOAD(1, kra, vra); NS_LSTORE(1, kra, vra); }
;   __syncthreads();
;   f32x16 s0, s1, du0, du1; bf16x8 P[4];
;   int st_cur = 0;
; DI void nsa_unit(const Params& p, lds8* lds, int bl, int g, int qb32) {
;     ...
;   const size_t rowbase = (size_t)bl * SEQ; const int q0 = qb32 * 32, qpos = q0 + r, blk = q0 >> 6;
;   bf16x8 qraw[4], qrot[4];
;   { const bf16_t* qp = QNS + (rowbase + qpos) * DM + hh * 64 + 8 * h;
; #pragma unroll
;     for (int ks = 0; ks < 4; ++ks) qraw[ks] = *(const bf16x8*)(qp + 16 * ks); }
;   const bf16_t* gp = GNS + (rowbase + qpos) * 64 + hh * 3;
;   const float g0 = bf2f(gp[0]), g1 = bf2f(gp[1]), g2 = bf2f(gp[2]);
;   f32x16 OT[2], O[2]; float m, l; const int grp = ((wid >> 2) ^ wid) & 1;
;   const bf16_t* kc = KC + (size_t)(bl * 2 + g) * 128 * 64; const bf16_t* vc = VC + (size_t)(bl * 2 + g) * 128 * 64;
;   CmpCap cap;
;   nsa_branch<0>(lds, kc, vc, 64, 3u, qraw, qpos, 0u, blk, O, m, l, tid, lane, grp, cap);
.LBB0_898:
	v_writelane_b32 v255, s88, 37
	s_movk_i32 s94, 0x84
	s_nop 0
	v_writelane_b32 v255, s89, 38
	s_or_b64 exec, exec, s[8:9]
	s_ashr_i32 s1, s0, 5
	v_mov_b32_e32 v136, v200
	s_sub_i32 s3, 63, s1
	s_bfe_u32 s71, s0, 0x40001
	s_and_b32 s70, s0, 1
	s_lshl_b32 s2, s3, 5
	v_readfirstlane_b32 s0, v136
	s_ashr_i32 s1, s0, 6
	v_and_b32_e32 v52, 31, v136
	s_lshl_b32 s0, s70, 3
	v_writelane_b32 v255, s1, 39
	s_add_i32 s0, s1, s0
	s_lshl_b32 s1, s71, 11
	v_or_b32_e32 v211, s2, v52
	v_add_u32_e32 v186, s1, v211
	v_readlane_b32 s8, v254, 51
	v_lshlrev_b64 v[0:1], 11, v[186:187]
	v_readlane_b32 s9, v254, 52
	s_lshl_b32 s96, s0, 6
	v_bfe_u32 v55, v136, 5, 1
	v_lshl_add_u64 v[0:1], s[8:9], 0, v[0:1]
	s_ashr_i32 s97, s96, 31
	v_lshl_add_u64 v[0:1], s[96:97], 1, v[0:1]
	v_lshlrev_b32_e32 v2, 4, v55
	v_mov_b32_e32 v3, v187
	v_lshl_add_u64 v[0:1], v[0:1], 0, v[2:3]
	v_readlane_b32 s8, v254, 57
	global_load_dwordx4 v[44:47], v[0:1], off
	global_load_dwordx4 v[36:39], v[0:1], off offset:32
	global_load_dwordx4 v[40:43], v[0:1], off offset:64
	global_load_dwordx4 v[32:35], v[0:1], off offset:96
	v_lshlrev_b64 v[0:1], 7, v[186:187]
	v_readlane_b32 s9, v254, 58
	v_writelane_b32 v255, s2, 40
	v_writelane_b32 v255, s1, 41
	v_lshl_add_u64 v[0:1], s[8:9], 0, v[0:1]
	s_mul_i32 s8, s0, 3
	s_ashr_i32 s9, s8, 31
	v_lshl_add_u64 v[0:1], s[8:9], 1, v[0:1]
	global_load_dword v209, v[0:1], off
	global_load_ushort v210, v[0:1], off offset:4
	v_cmp_gt_u32_e32 vcc, 2, v136
	s_and_saveexec_b64 s[8:9], vcc
	v_lshl_add_u32 v0, v136, 2, 0
	v_add_u32_e32 v0, 0x16d10, v0
	ds_write_b32 v0, v136
	s_or_b64 exec, exec, s[8:9]
	s_lshl_b32 s0, s70, 14
	s_lshl_b32 s6, s71, 15
	s_or_b32 s0, s6, s0
	v_readlane_b32 s1, v254, 55
	s_add_u32 s10, s1, s0
	v_readlane_b32 s1, v254, 56
	s_addc_u32 s11, s1, 0
	v_readlane_b32 s1, v254, 61
	v_and_b32_e32 v199, 63, v136
	s_add_u32 s8, s1, s0
	v_readlane_b32 s0, v254, 62
	s_addc_u32 s9, s0, 0
	v_lshlrev_b32_e32 v214, 2, v55
	v_lshrrev_b32_e32 v0, 2, v136
	v_lshlrev_b32_e32 v1, 3, v199
	s_add_i32 s0, 0, 0x16d10
	v_and_or_b32 v51, v0, 3, v214
	v_lshlrev_b32_e32 v0, 1, v199
	v_and_b32_e32 v1, 24, v1
	v_mov_b32_e32 v48, s0
	v_and_or_b32 v66, v0, 32, v1
	s_waitcnt lgkmcnt(0)
	s_barrier
	v_readlane_b32 s2, v255, 9
	ds_read_b32 v0, v48
	v_ashrrev_i32_e32 v212, 3, v136
	v_and_b32_e32 v54, 7, v136
	v_mov_b32_e32 v50, s2
	ds_read_b32 v9, v50
	v_lshlrev_b32_e32 v192, 4, v54
	v_mov_b32_e32 v193, v187
	s_movk_i32 s1, 0x90
	v_mul_lo_u32 v8, v212, s1
	v_mul_u32_u24_e32 v208, 0x90, v52
	v_lshl_add_u32 v213, v55, 4, v208
	s_waitcnt lgkmcnt(0)
	v_readfirstlane_b32 s6, v0
	v_readfirstlane_b32 s77, v9
	v_add3_u32 v215, 0, v8, v192
	s_nop 0
	v_lshl_add_u32 v0, s6, 6, v212
	s_nop 0
	v_lshl_add_u32 v10, s77, 6, v212
	v_ashrrev_i32_e32 v1, 31, v0
	v_ashrrev_i32_e32 v11, 31, v10
	v_lshlrev_b64 v[4:5], 7, v[0:1]
	v_lshlrev_b64 v[12:13], 7, v[10:11]
	v_lshl_add_u64 v[0:1], s[10:11], 0, v[4:5]
	v_lshl_add_u64 v[0:1], v[0:1], 0, v[192:193]
	v_lshl_add_u64 v[4:5], s[8:9], 0, v[4:5]
	global_load_dwordx4 v[0:3], v[0:1], off
	v_lshl_add_u64 v[4:5], v[4:5], 0, v[192:193]
	global_load_dwordx4 v[4:7], v[4:5], off
	v_lshl_add_u64 v[8:9], s[10:11], 0, v[12:13]
	v_lshl_add_u64 v[8:9], v[8:9], 0, v[192:193]
	v_lshl_add_u64 v[12:13], s[8:9], 0, v[12:13]
	global_load_dwordx4 v[8:11], v[8:9], off
	v_lshl_add_u64 v[12:13], v[12:13], 0, v[192:193]
	global_load_dwordx4 v[12:15], v[12:13], off
	s_waitcnt vmcnt(3)
	ds_write_b128 v215, v[0:3]
	s_waitcnt vmcnt(2)
	ds_write_b128 v215, v[4:7] offset:9216
	s_waitcnt vmcnt(1)
	ds_write_b128 v215, v[8:11] offset:18432
	s_waitcnt vmcnt(0)
	ds_write_b128 v215, v[12:15] offset:27648
	v_subrev_u32_e32 v0, 31, v211
	v_and_b32_e32 v1, 64, v202
	v_ashrrev_i32_e32 v121, 4, v0
	v_xor_b32_e32 v0, 32, v202
	v_add_u32_e32 v53, 64, v1
	v_cmp_lt_i32_e32 vcc, v0, v53
	s_waitcnt lgkmcnt(0)
	s_barrier
	v_cndmask_b32_e32 v0, v202, v0, vcc
	v_lshlrev_b32_e32 v193, 2, v0
	v_add_u32_e32 v134, 0, v213
	ds_read_b128 v[56:59], v134
	ds_read_b128 v[60:63], v134 offset:32
	ds_read_b128 v[68:71], v134 offset:4608
	ds_read_b128 v[72:75], v134 offset:4640
	ds_read_b128 v[76:79], v134 offset:64
	ds_read_b128 v[80:83], v134 offset:96
	ds_read_b128 v[84:87], v134 offset:4672
	ds_read_b128 v[88:91], v134 offset:4704
	s_setprio 1
	s_mov_b32 s77, s76
	s_mov_b32 s78, s76
	s_mov_b32 s79, s76
	s_mov_b32 s80, s76
	s_mov_b32 s81, s76
	s_mov_b32 s82, s76
	s_mov_b32 s83, s76
	s_mov_b32 s84, s76
	s_mov_b32 s85, s76
	s_mov_b32 s86, s76
	s_mov_b32 s87, s76
	s_mov_b32 s88, s76
	s_mov_b32 s89, s76
	s_mov_b32 s90, s76
	s_mov_b32 s91, s76
	v_mov_b64_e32 v[0:1], s[76:77]
	v_mov_b64_e32 v[2:3], s[78:79]
	v_mov_b64_e32 v[4:5], s[80:81]
	v_mov_b64_e32 v[6:7], s[82:83]
	v_mov_b64_e32 v[8:9], s[84:85]
	v_mov_b64_e32 v[10:11], s[86:87]
	v_mov_b64_e32 v[12:13], s[88:89]
	v_mov_b64_e32 v[14:15], s[90:91]
	s_waitcnt lgkmcnt(7)
	s_nop 0
	v_mfma_f32_32x32x16_bf16 v[16:31], v[56:59], v[44:47], v[0:15]
	s_waitcnt lgkmcnt(5)
	v_mfma_f32_32x32x16_bf16 v[0:15], v[68:71], v[44:47], v[0:15]
	v_mfma_f32_32x32x16_bf16 v[16:31], v[60:63], v[36:39], v[16:31]
	s_waitcnt lgkmcnt(4)
	v_mfma_f32_32x32x16_bf16 v[0:15], v[72:75], v[36:39], v[0:15]
	s_waitcnt lgkmcnt(3)
	v_mfma_f32_32x32x16_bf16 v[16:31], v[76:79], v[40:43], v[16:31]
	s_waitcnt lgkmcnt(1)
	v_mfma_f32_32x32x16_bf16 v[0:15], v[84:87], v[40:43], v[0:15]
	v_mfma_f32_32x32x16_bf16 v[16:31], v[80:83], v[32:35], v[16:31]
	s_waitcnt lgkmcnt(0)
	v_mfma_f32_32x32x16_bf16 v[0:15], v[88:91], v[32:35], v[0:15]
	s_setprio 0
	ds_read_b32 v48, v48
	s_mov_b32 s85, 0xefa18f08
	v_mad_u32_u24 v216, v51, s1, v66
	v_add_u32_e32 v96, 0, v216
	s_waitcnt lgkmcnt(0)
; #define LAS __attribute__((address_space(3)))
; DI float rowmax32(const f32x16& s0, const f32x16& s1) {
;   float a = fmaxf(fmaxf(s0[0], s0[1]), s1[0]), b = fmaxf(fmaxf(s0[2], s0[3]), s1[1]); a = fmaxf(fmaxf(a, s1[2]), s1[3]);
; #pragma unroll
;   for (int r = 4; r < 16; r += 4) { a = fmaxf(fmaxf(a, s0[r]), s0[r + 1]); b = fmaxf(fmaxf(b, s0[r + 2]), s0[r + 3]); a = fmaxf(fmaxf(a, s1[r]), s1[r + 1]); b = fmaxf(fmaxf(b, s1[r + 2]), s1[r + 3]); }
;   const float m = fmaxf(a, b);
;   return fmaxf(m, __shfl_xor(m, 32));
; }
; template <int MODE, int SLOT> DI void ns_valu(volatile LAS int* jl, int t, int ntl, int qpos, int h, int blk, f32x16& s0, f32x16& s1, f32x16& du0, f32x16& du1, f32x16 (&O)[2], float& muse, float& l, bf16x8 (&P)[4], CmpCap& cap) {
;     if (t < ntl) {
;       const int j = __builtin_amdgcn_readfirstlane(jl[t]);
;       if (MODE == 0) {
;         const int lim = ((qpos - 31) >> 4) - 64 * j - 4 * h;
; #pragma unroll
;         for (int i = 0; i < 16; ++i) { const int ci = (i & 3) + 8 * (i >> 2); if (ci > lim) s0[i] = NEG; if (ci + 32 > lim) s1[i] = NEG; }
	v_readfirstlane_b32 s6, v48
	s_nop 1
	v_lshl_or_b32 v48, s6, 6, v214
	v_sub_u32_e32 v48, v121, v48
	v_cmp_gt_i32_e64 s[64:65], 26, v48
	v_cmp_gt_i32_e64 s[68:69], 27, v48
	v_cmp_gt_i32_e64 s[60:61], 25, v48
	s_and_b64 s[64:65], s[68:69], s[64:65]
	v_cmp_gt_i32_e64 s[56:57], 24, v48
	s_and_b64 s[60:61], s[64:65], s[60:61]
	v_cmp_gt_i32_e64 s[52:53], 19, v48
	s_and_b64 s[56:57], s[60:61], s[56:57]
	v_cmp_gt_i32_e64 s[48:49], 18, v48
	s_and_b64 s[52:53], s[56:57], s[52:53]
	v_cmp_gt_i32_e64 s[44:45], 17, v48
	s_and_b64 s[48:49], s[52:53], s[48:49]
	v_cmp_gt_i32_e64 s[40:41], 16, v48
	s_and_b64 s[44:45], s[48:49], s[44:45]
	v_cmp_gt_i32_e64 s[36:37], 11, v48
	s_and_b64 s[40:41], s[44:45], s[40:41]
	v_cmp_gt_i32_e64 s[30:31], 10, v48
	s_and_b64 s[36:37], s[40:41], s[36:37]
	v_cmp_gt_i32_e64 s[26:27], 9, v48
	s_and_b64 s[30:31], s[36:37], s[30:31]
	v_cmp_gt_i32_e64 s[22:23], 8, v48
	s_and_b64 s[26:27], s[30:31], s[26:27]
	v_cmp_gt_i32_e64 s[20:21], 3, v48
	s_and_b64 s[22:23], s[26:27], s[22:23]
	v_cmp_gt_i32_e64 s[18:19], 2, v48
	s_and_b64 s[20:21], s[22:23], s[20:21]
	v_cmp_gt_i32_e64 s[16:17], 1, v48
	s_and_b64 s[18:19], s[20:21], s[18:19]
	v_cmp_gt_i32_e64 s[14:15], 0, v48
	s_and_b64 s[16:17], s[18:19], s[16:17]
	s_and_b64 s[14:15], s[16:17], s[14:15]
	v_cmp_gt_i32_e64 s[66:67], 58, v48
	v_cndmask_b32_e64 v16, v16, v207, s[14:15]
	v_cmp_gt_i32_e64 s[14:15], 59, v48
	v_cmp_gt_i32_e64 s[62:63], 57, v48
	v_cmp_gt_i32_e64 s[58:59], 56, v48
	v_cndmask_b32_e64 v15, v15, v207, s[14:15]
	s_and_b64 s[14:15], s[14:15], s[66:67]
	v_cndmask_b32_e64 v14, v14, v207, s[14:15]
	s_and_b64 s[14:15], s[14:15], s[62:63]
	v_cmp_gt_i32_e64 s[54:55], 51, v48
	v_cndmask_b32_e64 v13, v13, v207, s[14:15]
	s_and_b64 s[14:15], s[14:15], s[58:59]
	v_cmp_gt_i32_e64 s[50:51], 50, v48
	v_cndmask_b32_e64 v12, v12, v207, s[14:15]
	s_and_b64 s[14:15], s[14:15], s[54:55]
	v_cmp_gt_i32_e64 s[46:47], 49, v48
	v_cndmask_b32_e64 v11, v11, v207, s[14:15]
	s_and_b64 s[14:15], s[14:15], s[50:51]
	v_cmp_gt_i32_e64 s[42:43], 48, v48
	v_cndmask_b32_e64 v10, v10, v207, s[14:15]
	s_and_b64 s[14:15], s[14:15], s[46:47]
	v_cmp_gt_i32_e64 s[38:39], 43, v48
	v_cndmask_b32_e64 v9, v9, v207, s[14:15]
	s_and_b64 s[14:15], s[14:15], s[42:43]
	v_cmp_gt_i32_e64 s[34:35], 42, v48
	v_cndmask_b32_e64 v8, v8, v207, s[14:15]
	s_and_b64 s[14:15], s[14:15], s[38:39]
	v_cmp_gt_i32_e64 s[28:29], 41, v48
	v_cndmask_b32_e64 v7, v7, v207, s[14:15]
	s_and_b64 s[14:15], s[14:15], s[34:35]
	v_cmp_gt_i32_e64 s[24:25], 40, v48
	v_cndmask_b32_e64 v6, v6, v207, s[14:15]
	s_and_b64 s[14:15], s[14:15], s[28:29]
	v_cmp_gt_i32_e64 s[12:13], 35, v48
	v_cndmask_b32_e64 v5, v5, v207, s[14:15]
	s_and_b64 s[14:15], s[14:15], s[24:25]
	v_cmp_gt_i32_e64 s[10:11], 34, v48
	s_and_b64 s[12:13], s[14:15], s[12:13]
	v_cmp_gt_i32_e64 s[8:9], 33, v48
	s_and_b64 s[10:11], s[12:13], s[10:11]
	v_cmp_gt_i32_e32 vcc, 32, v48
	v_cndmask_b32_e64 v17, v17, v207, s[16:17]
	s_and_b64 s[8:9], s[10:11], s[8:9]
	s_and_b64 vcc, s[8:9], vcc
	v_max_f32_e32 v48, v17, v17
	v_max_f32_e32 v49, v16, v16
	v_cndmask_b32_e64 v19, v19, v207, s[20:21]
	v_cndmask_b32_e64 v18, v18, v207, s[18:19]
	v_cndmask_b32_e64 v2, v2, v207, s[10:11]
	v_cndmask_b32_e64 v1, v1, v207, s[8:9]
	v_cndmask_b32_e32 v0, v0, v207, vcc
	v_max_f32_e32 v48, v49, v48
	v_cndmask_b32_e64 v23, v23, v207, s[36:37]
	v_cndmask_b32_e64 v22, v22, v207, s[30:31]
	v_cndmask_b32_e64 v20, v20, v207, s[22:23]
	v_cndmask_b32_e64 v3, v3, v207, s[12:13]
	v_max3_f32 v49, v18, v19, v1
	v_max3_f32 v48, v48, v0, v2
	v_cndmask_b32_e64 v21, v21, v207, s[26:27]
	v_cndmask_b32_e64 v4, v4, v207, s[14:15]
	v_max3_f32 v48, v48, v3, v20
	v_max3_f32 v49, v49, v22, v23
	v_cndmask_b32_e64 v27, v27, v207, s[52:53]
	v_cndmask_b32_e64 v26, v26, v207, s[48:49]
	v_cndmask_b32_e64 v24, v24, v207, s[40:41]
	v_max3_f32 v48, v48, v21, v4
	v_max3_f32 v49, v49, v6, v7
	v_cndmask_b32_e64 v25, v25, v207, s[44:45]
	v_max3_f32 v48, v48, v5, v24
	v_max3_f32 v49, v49, v26, v27
	v_cndmask_b32_e64 v31, v31, v207, s[68:69]
	v_cndmask_b32_e64 v30, v30, v207, s[64:65]
	v_cndmask_b32_e64 v28, v28, v207, s[56:57]
	v_max3_f32 v48, v48, v25, v8
	v_max3_f32 v49, v49, v10, v11
	v_cndmask_b32_e64 v29, v29, v207, s[60:61]
	v_max3_f32 v48, v48, v9, v28
	v_max3_f32 v49, v49, v30, v31
	v_max3_f32 v48, v48, v29, v12
	v_max3_f32 v49, v49, v14, v15
	v_max3_f32 v48, v48, v13, v49
	ds_bpermute_b32 v49, v193, v48
	s_waitcnt lgkmcnt(0)
; template <int VSTR, int NDVB> DI void pv64(f32x16 (&O)[NDVB], const lds8* vp, const bf16x8 (&P)[4]) {
;   bf16x8 f[2][NDVB];
; #pragma unroll
;   for (int d = 0; d < NDVB; ++d) { const s16x4 lo = trrd(vp + d * 64), hi = trrd(vp + 8 * VSTR + d * 64); f[0][d] = __builtin_shufflevector(lo, hi, 0, 1, 2, 3, 4, 5, 6, 7); }
; #pragma unroll
;   for (int kk = 0; kk < 4; ++kk) {
;     if (kk < 3) {
; #pragma unroll
;       for (int d = 0; d < NDVB; ++d) { const s16x4 lo = trrd(vp + (16 * (kk + 1)) * VSTR + d * 64), hi = trrd(vp + (16 * (kk + 1) + 8) * VSTR + d * 64);
;         f[(kk + 1) & 1][d] = __builtin_shufflevector(lo, hi, 0, 1, 2, 3, 4, 5, 6, 7); }
;     }
;     SBAR();
; template <int NDVB, bool HAS_NEXT> DI void softmax_def(f32x16& sa0, f32x16& sa1, f32x16& sb0, f32x16& sb1, f32x16 (&O)[NDVB], float& muse, float& l, bool first, bf16x8 (&P)[4], bool check = true) {
;   float mx = 0.f;
;   if (check) mx = rowmax32(sa0, sa1);
;   if (check && (first || __any(mx > 8.f))) {
;     float dl = first ? mx : fmaxf(mx, 0.f);
;     if (mx < -1e29f) dl = 0.f;
;     const float alpha = __builtin_amdgcn_exp2f(-dl);
;     muse += dl; l *= alpha;
; #pragma unroll
;     for (int i = 0; i < 16; ++i) { sa0[i] -= dl; sa1[i] -= dl; }
;     if (HAS_NEXT) {
; #pragma unroll
;       for (int i = 0; i < 16; ++i) { sb0[i] -= dl; sb1[i] -= dl; }
;     }
; #pragma unroll
;     for (int d = 0; d < NDVB; ++d)
; #pragma unroll
;       for (int i = 0; i < 16; ++i) O[d][i] *= alpha;
;   }
;   float sum = 0.f;
; #pragma unroll
;   for (int i = 0; i < 16; ++i) { sa0[i] = __builtin_amdgcn_exp2f(sa0[i]); sum += sa0[i]; }
; #pragma unroll
;   for (int i = 0; i < 16; ++i) { sa1[i] = __builtin_amdgcn_exp2f(sa1[i]); sum += sa1[i]; }
;   l += sum;
;   u32x4 w;
;   w.x = cvtpk(sa0[0], sa0[1]); w.y = cvtpk(sa0[2], sa0[3]); w.z = cvtpk(sa0[4], sa0[5]); w.w = cvtpk(sa0[6], sa0[7]); P[0] = __builtin_bit_cast(bf16x8, w);
;   w.x = cvtpk(sa0[8], sa0[9]); w.y = cvtpk(sa0[10], sa0[11]); w.z = cvtpk(sa0[12], sa0[13]); w.w = cvtpk(sa0[14], sa0[15]); P[1] = __builtin_bit_cast(bf16x8, w);
;   w.x = cvtpk(sa1[0], sa1[1]); w.y = cvtpk(sa1[2], sa1[3]); w.z = cvtpk(sa1[4], sa1[5]); w.w = cvtpk(sa1[6], sa1[7]); P[2] = __builtin_bit_cast(bf16x8, w);
;   w.x = cvtpk(sa1[8], sa1[9]); w.y = cvtpk(sa1[10], sa1[11]); w.z = cvtpk(sa1[12], sa1[13]); w.w = cvtpk(sa1[14], sa1[15]); P[3] = __builtin_bit_cast(bf16x8, w);
; }
	v_max_f32_e32 v49, v49, v49
	v_max_f32_e32 v48, v48, v49
	v_cmp_ngt_f32_e32 vcc, s85, v48
	s_nop 1
	v_cndmask_b32_e32 v65, 0, v48, vcc
	v_sub_f32_e32 v16, v16, v65
	v_sub_f32_e32 v17, v17, v65
	v_exp_f32_e32 v97, v16
	v_sub_f32_e32 v18, v18, v65
	v_exp_f32_e32 v98, v17
	v_sub_f32_e32 v19, v19, v65
	v_exp_f32_e32 v99, v18
	v_sub_f32_e32 v20, v20, v65
	v_exp_f32_e32 v56, v19
	v_sub_f32_e32 v21, v21, v65
	v_add_f32_e32 v16, 0, v97
	v_exp_f32_e32 v100, v20
	v_sub_f32_e32 v22, v22, v65
	v_add_f32_e32 v16, v98, v16
	v_exp_f32_e32 v101, v21
	v_sub_f32_e32 v23, v23, v65
	v_add_f32_e32 v16, v99, v16
	v_exp_f32_e32 v102, v22
	v_sub_f32_e32 v24, v24, v65
	v_add_f32_e32 v16, v56, v16
	v_exp_f32_e32 v57, v23
	v_sub_f32_e32 v25, v25, v65
	v_add_f32_e32 v16, v100, v16
	v_exp_f32_e32 v103, v24
	v_sub_f32_e32 v26, v26, v65
	v_add_f32_e32 v16, v101, v16
	v_exp_f32_e32 v104, v25
	v_sub_f32_e32 v27, v27, v65
	v_add_f32_e32 v16, v102, v16
	v_exp_f32_e32 v105, v26
	v_sub_f32_e32 v28, v28, v65
	v_add_f32_e32 v16, v57, v16
	v_exp_f32_e32 v58, v27
	v_sub_f32_e32 v29, v29, v65
	v_add_f32_e32 v16, v103, v16
	v_exp_f32_e32 v106, v28
	v_sub_f32_e32 v30, v30, v65
	v_add_f32_e32 v16, v104, v16
	v_exp_f32_e32 v107, v29
	v_sub_f32_e32 v31, v31, v65
	v_add_f32_e32 v16, v105, v16
	v_exp_f32_e32 v108, v30
	v_sub_f32_e32 v0, v0, v65
	v_add_f32_e32 v16, v58, v16
	v_exp_f32_e32 v59, v31
	v_sub_f32_e32 v1, v1, v65
	v_add_f32_e32 v16, v106, v16
	v_exp_f32_e32 v109, v0
	v_sub_f32_e32 v2, v2, v65
	v_add_f32_e32 v16, v107, v16
	v_exp_f32_e32 v110, v1
	v_sub_f32_e32 v3, v3, v65
	v_add_f32_e32 v16, v108, v16
	v_exp_f32_e32 v111, v2
	v_sub_f32_e32 v4, v4, v65
	v_add_f32_e32 v16, v59, v16
	v_exp_f32_e32 v60, v3
	v_sub_f32_e32 v5, v5, v65
	v_add_f32_e32 v0, v109, v16
	v_exp_f32_e32 v112, v4
	v_sub_f32_e32 v6, v6, v65
	v_add_f32_e32 v0, v110, v0
	v_exp_f32_e32 v113, v5
	v_sub_f32_e32 v7, v7, v65
	v_add_f32_e32 v0, v111, v0
	v_exp_f32_e32 v114, v6
	v_sub_f32_e32 v8, v8, v65
	v_add_f32_e32 v0, v60, v0
	v_exp_f32_e32 v61, v7
	v_sub_f32_e32 v9, v9, v65
	v_add_f32_e32 v0, v112, v0
	v_exp_f32_e32 v115, v8
	v_sub_f32_e32 v10, v10, v65
	v_sub_f32_e32 v12, v12, v65
	v_sub_f32_e32 v13, v13, v65
	v_sub_f32_e32 v14, v14, v65
	v_sub_f32_e32 v15, v15, v65
	v_add_f32_e32 v0, v113, v0
	v_exp_f32_e32 v116, v9
	v_sub_f32_e32 v11, v11, v65
	v_add_f32_e32 v0, v114, v0
	v_exp_f32_e32 v117, v10
	v_exp_f32_e32 v118, v12
	v_exp_f32_e32 v119, v13
	v_exp_f32_e32 v120, v14
	v_exp_f32_e32 v63, v15
	ds_read_b64_tr_b16 v[12:13], v96 offset:9216
	ds_read_b64_tr_b16 v[14:15], v96 offset:10368
	ds_read_b64_tr_b16 v[18:19], v96 offset:10432
	ds_read_b64_tr_b16 v[16:17], v96 offset:9280
	ds_read_b64_tr_b16 v[20:21], v96 offset:11520
	ds_read_b64_tr_b16 v[22:23], v96 offset:12672
	ds_read_b64_tr_b16 v[26:27], v96 offset:12736
	ds_read_b64_tr_b16 v[24:25], v96 offset:11584
	v_add_f32_e32 v0, v61, v0
	v_exp_f32_e32 v62, v11
	v_add_f32_e32 v0, v115, v0
	v_add_f32_e32 v0, v116, v0
	v_add_f32_e32 v0, v117, v0
	v_exp_f32_e64 v48, -v65
	v_add_f32_e32 v0, v62, v0
	v_add_f32_e32 v0, v118, v0
	v_add_f32_e32 v0, v119, v0
	v_add_f32_e32 v0, v120, v0
	v_mul_f32_e32 v64, 0, v48
	v_add_f32_e32 v186, v63, v0
	v_pk_add_f32 v[48:49], v[64:65], v[186:187]
	v_cvt_pk_bf16_f32 v0, v97, v98
	v_cvt_pk_bf16_f32 v2, v100, v101
	v_cvt_pk_bf16_f32 v3, v102, v57
	v_cvt_pk_bf16_f32 v4, v103, v104
	v_cvt_pk_bf16_f32 v5, v105, v58
	v_cvt_pk_bf16_f32 v6, v106, v107
	v_cvt_pk_bf16_f32 v7, v108, v59
	v_cvt_pk_bf16_f32 v8, v109, v110
	v_cvt_pk_bf16_f32 v9, v111, v60
	v_cvt_pk_bf16_f32 v10, v112, v113
	v_cvt_pk_bf16_f32 v11, v114, v61
	v_cvt_pk_bf16_f32 v28, v115, v116
	v_cvt_pk_bf16_f32 v29, v117, v62
	v_cvt_pk_bf16_f32 v30, v118, v119
	v_cvt_pk_bf16_f32 v31, v120, v63
	v_cvt_pk_bf16_f32 v1, v99, v56
	s_setprio 1
	v_mov_b32_e32 v65, v64
	v_mov_b64_e32 v[66:67], v[64:65]
	v_mov_b64_e32 v[68:69], v[64:65]
	v_mov_b64_e32 v[70:71], v[64:65]
	v_mov_b64_e32 v[72:73], v[64:65]
	v_mov_b64_e32 v[74:75], v[64:65]
	v_mov_b64_e32 v[76:77], v[64:65]
	v_mov_b64_e32 v[78:79], v[64:65]
	s_waitcnt lgkmcnt(6)
	s_nop 0
	v_mfma_f32_32x32x16_bf16 v[80:95], v[12:15], v[0:3], v[64:79]
	s_waitcnt lgkmcnt(4)
	v_mfma_f32_32x32x16_bf16 v[64:79], v[16:19], v[0:3], v[64:79]
	s_setprio 0
	ds_read_b64_tr_b16 v[0:1], v96 offset:13824
	ds_read_b64_tr_b16 v[2:3], v96 offset:14976
	ds_read_b64_tr_b16 v[14:15], v96 offset:15040
	ds_read_b64_tr_b16 v[12:13], v96 offset:13888
	s_setprio 1
	s_waitcnt lgkmcnt(6)
	v_mfma_f32_32x32x16_bf16 v[80:95], v[20:23], v[4:7], v[80:95]
	s_waitcnt lgkmcnt(4)
	v_mfma_f32_32x32x16_bf16 v[64:79], v[24:27], v[4:7], v[64:79]
	s_setprio 0
	ds_read_b64_tr_b16 v[4:5], v96 offset:16128
	ds_read_b64_tr_b16 v[6:7], v96 offset:17280
	ds_read_b64_tr_b16 v[18:19], v96 offset:17344
	ds_read_b64_tr_b16 v[16:17], v96 offset:16192
	s_setprio 1
	s_waitcnt lgkmcnt(6)
	v_mfma_f32_32x32x16_bf16 v[80:95], v[0:3], v[8:11], v[80:95]
	s_waitcnt lgkmcnt(4)
	v_mfma_f32_32x32x16_bf16 v[64:79], v[12:15], v[8:11], v[64:79]
	s_setprio 0
	s_setprio 1
	s_waitcnt lgkmcnt(2)
	v_mfma_f32_32x32x16_bf16 v[80:95], v[4:7], v[28:31], v[80:95]
	s_waitcnt lgkmcnt(0)
	v_mfma_f32_32x32x16_bf16 v[64:79], v[16:19], v[28:31], v[64:79]
	s_setprio 0
	s_barrier
; #define LAS __attribute__((address_space(3)))
; template <int MODE, int SLOT> DI void ns_valu(volatile LAS int* jl, int t, int ntl, int qpos, int h, int blk, f32x16& s0, f32x16& s1, f32x16& du0, f32x16& du1, f32x16 (&O)[2], float& muse, float& l, bf16x8 (&P)[4], CmpCap& cap) {
;     if (t < ntl) {
;       const int j = __builtin_amdgcn_readfirstlane(jl[t]);
;       if (MODE == 0) {
;         const int lim = ((qpos - 31) >> 4) - 64 * j - 4 * h;
; #pragma unroll
;         for (int i = 0; i < 16; ++i) { const int ci = (i & 3) + 8 * (i >> 2); if (ci > lim) s0[i] = NEG; if (ci + 32 > lim) s1[i] = NEG; }
; template <int MODE>
; DI void nsa_branch(lds8* lds, const bf16_t* kg, const bf16_t* vg, int pitch, unsigned tiles, const bf16x8 (&q)[4], int qpos, unsigned mybits, int blk,
;                    f32x16 (&O)[2], float& muse, float& l, int tid, int lane, int grp, CmpCap& cap) {
;     ...
;   __syncthreads();
;   f32x16 s0, s1, du0, du1; bf16x8 P[4];
;   int st_cur = 0;
	ds_read_b128 v[122:125], v134 offset:18432
	ds_read_b128 v[126:129], v134 offset:18464
	ds_read_b128 v[130:133], v134 offset:23040
	ds_read_b128 v[138:141], v134 offset:23072
	ds_read_b128 v[142:145], v134 offset:18496
	ds_read_b128 v[146:149], v134 offset:18528
	ds_read_b128 v[150:153], v134 offset:23104
	ds_read_b128 v[154:157], v134 offset:23136
	v_xor_b32_e32 v0, 0x80000000, v49
	v_mov_b32_e32 v2, v0
	v_mov_b32_e32 v3, v0
	v_mov_b32_e32 v4, v0
	v_mov_b32_e32 v5, v0
	v_mov_b32_e32 v6, v0
	v_mov_b32_e32 v7, v0
	v_mov_b32_e32 v8, v0
	v_mov_b32_e32 v9, v0
	v_mov_b32_e32 v10, v0
	v_mov_b32_e32 v11, v0
	v_mov_b32_e32 v12, v0
	v_mov_b32_e32 v13, v0
	v_mov_b32_e32 v14, v0
	v_mov_b32_e32 v15, v0
	v_mov_b32_e32 v1, v0
	s_setprio 1
	s_waitcnt lgkmcnt(7)
	v_mfma_f32_32x32x16_bf16 v[16:31], v[122:125], v[44:47], v[0:15]
	s_waitcnt lgkmcnt(5)
	v_mfma_f32_32x32x16_bf16 v[0:15], v[130:133], v[44:47], v[0:15]
	v_mfma_f32_32x32x16_bf16 v[16:31], v[126:129], v[36:39], v[16:31]
	s_waitcnt lgkmcnt(4)
	v_mfma_f32_32x32x16_bf16 v[0:15], v[138:141], v[36:39], v[0:15]
	s_waitcnt lgkmcnt(3)
	v_mfma_f32_32x32x16_bf16 v[16:31], v[142:145], v[40:43], v[16:31]
	s_waitcnt lgkmcnt(1)
	v_mfma_f32_32x32x16_bf16 v[0:15], v[150:153], v[40:43], v[0:15]
	v_mfma_f32_32x32x16_bf16 v[16:31], v[146:149], v[32:35], v[16:31]
	s_waitcnt lgkmcnt(0)
	v_mfma_f32_32x32x16_bf16 v[0:15], v[154:157], v[32:35], v[0:15]
	s_setprio 0
	ds_read_b32 v50, v50
	s_waitcnt lgkmcnt(0)
	v_readfirstlane_b32 s6, v50
	s_nop 1
	v_lshl_or_b32 v50, s6, 6, v214
	v_sub_u32_e32 v121, v121, v50
	v_cmp_gt_i32_e64 s[64:65], 26, v121
	v_cmp_gt_i32_e64 s[68:69], 27, v121
	v_cmp_gt_i32_e64 s[60:61], 25, v121
	s_and_b64 s[64:65], s[68:69], s[64:65]
	v_cmp_gt_i32_e64 s[56:57], 24, v121
	s_and_b64 s[60:61], s[64:65], s[60:61]
	v_cmp_gt_i32_e64 s[52:53], 19, v121
	s_and_b64 s[56:57], s[60:61], s[56:57]
	v_cmp_gt_i32_e64 s[48:49], 18, v121
	s_and_b64 s[52:53], s[56:57], s[52:53]
	v_cmp_gt_i32_e64 s[44:45], 17, v121
	s_and_b64 s[48:49], s[52:53], s[48:49]
	v_cmp_gt_i32_e64 s[40:41], 16, v121
	s_and_b64 s[44:45], s[48:49], s[44:45]
	v_cmp_gt_i32_e64 s[36:37], 11, v121
	s_and_b64 s[40:41], s[44:45], s[40:41]
	v_cmp_gt_i32_e64 s[30:31], 10, v121
	s_and_b64 s[36:37], s[40:41], s[36:37]
	v_cmp_gt_i32_e64 s[26:27], 9, v121
	s_and_b64 s[30:31], s[36:37], s[30:31]
	v_cmp_gt_i32_e64 s[22:23], 8, v121
	s_and_b64 s[26:27], s[30:31], s[26:27]
	v_cmp_gt_i32_e64 s[20:21], 3, v121
	s_and_b64 s[22:23], s[26:27], s[22:23]
	v_cmp_gt_i32_e64 s[18:19], 2, v121
	s_and_b64 s[20:21], s[22:23], s[20:21]
	v_cmp_gt_i32_e64 s[16:17], 1, v121
	s_and_b64 s[18:19], s[20:21], s[18:19]
	v_cmp_gt_i32_e64 s[14:15], 0, v121
	s_and_b64 s[16:17], s[18:19], s[16:17]
	s_and_b64 s[14:15], s[16:17], s[14:15]
	v_cmp_gt_i32_e64 s[66:67], 58, v121
	v_cndmask_b32_e64 v50, v16, v207, s[14:15]
	v_cmp_gt_i32_e64 s[14:15], 59, v121
	v_cmp_gt_i32_e64 s[62:63], 57, v121
	v_cmp_gt_i32_e64 s[58:59], 56, v121
	v_cndmask_b32_e64 v15, v15, v207, s[14:15]
	s_and_b64 s[14:15], s[14:15], s[66:67]
	v_cndmask_b32_e64 v14, v14, v207, s[14:15]
	s_and_b64 s[14:15], s[14:15], s[62:63]
	v_cmp_gt_i32_e64 s[54:55], 51, v121
	v_cndmask_b32_e64 v13, v13, v207, s[14:15]
	s_and_b64 s[14:15], s[14:15], s[58:59]
	v_cmp_gt_i32_e64 s[50:51], 50, v121
	v_cndmask_b32_e64 v12, v12, v207, s[14:15]
	s_and_b64 s[14:15], s[14:15], s[54:55]
	v_cmp_gt_i32_e64 s[46:47], 49, v121
	v_cndmask_b32_e64 v11, v11, v207, s[14:15]
	s_and_b64 s[14:15], s[14:15], s[50:51]
	v_cmp_gt_i32_e64 s[42:43], 48, v121
	v_cndmask_b32_e64 v10, v10, v207, s[14:15]
	s_and_b64 s[14:15], s[14:15], s[46:47]
	v_cmp_gt_i32_e64 s[38:39], 43, v121
	v_cndmask_b32_e64 v9, v9, v207, s[14:15]
	s_and_b64 s[14:15], s[14:15], s[42:43]
	v_cmp_gt_i32_e64 s[34:35], 42, v121
	v_cndmask_b32_e64 v8, v8, v207, s[14:15]
	s_and_b64 s[14:15], s[14:15], s[38:39]
	v_cmp_gt_i32_e64 s[28:29], 41, v121
	v_cndmask_b32_e64 v7, v7, v207, s[14:15]
	s_and_b64 s[14:15], s[14:15], s[34:35]
	v_cmp_gt_i32_e64 s[24:25], 40, v121
	v_cndmask_b32_e64 v6, v6, v207, s[14:15]
	s_and_b64 s[14:15], s[14:15], s[28:29]
	v_cmp_gt_i32_e64 s[12:13], 35, v121
	v_cndmask_b32_e64 v5, v5, v207, s[14:15]
	s_and_b64 s[14:15], s[14:15], s[24:25]
	v_cmp_gt_i32_e64 s[10:11], 34, v121
	s_and_b64 s[12:13], s[14:15], s[12:13]
	v_cmp_gt_i32_e64 s[8:9], 33, v121
	s_and_b64 s[10:11], s[12:13], s[10:11]
	v_cmp_gt_i32_e32 vcc, 32, v121
	s_and_b64 s[8:9], s[10:11], s[8:9]
	v_cndmask_b32_e64 v51, v17, v207, s[16:17]
	s_and_b64 vcc, s[8:9], vcc
	v_cndmask_b32_e64 v17, v1, v207, s[8:9]
	v_cndmask_b32_e32 v16, v0, v207, vcc
	v_max_f32_e32 v0, v51, v51
	v_max_f32_e32 v1, v50, v50
	v_cndmask_b32_e64 v19, v19, v207, s[20:21]
	v_cndmask_b32_e64 v18, v18, v207, s[18:19]
	v_cndmask_b32_e64 v2, v2, v207, s[10:11]
	v_max_f32_e32 v0, v1, v0
	v_cndmask_b32_e64 v23, v23, v207, s[36:37]
	v_cndmask_b32_e64 v22, v22, v207, s[30:31]
	v_cndmask_b32_e64 v20, v20, v207, s[22:23]
	v_cndmask_b32_e64 v3, v3, v207, s[12:13]
	v_max3_f32 v1, v18, v19, v17
	v_max3_f32 v0, v0, v16, v2
	v_cndmask_b32_e64 v21, v21, v207, s[26:27]
	v_cndmask_b32_e64 v4, v4, v207, s[14:15]
	v_max3_f32 v0, v0, v3, v20
	v_max3_f32 v1, v1, v22, v23
	v_cndmask_b32_e64 v27, v27, v207, s[52:53]
	v_cndmask_b32_e64 v26, v26, v207, s[48:49]
	v_cndmask_b32_e64 v24, v24, v207, s[40:41]
	v_max3_f32 v0, v0, v21, v4
	v_max3_f32 v1, v1, v6, v7
	v_cndmask_b32_e64 v25, v25, v207, s[44:45]
	v_max3_f32 v0, v0, v5, v24
	v_max3_f32 v1, v1, v26, v27
	v_cndmask_b32_e64 v31, v31, v207, s[68:69]
	v_cndmask_b32_e64 v30, v30, v207, s[64:65]
	v_cndmask_b32_e64 v28, v28, v207, s[56:57]
	v_max3_f32 v0, v0, v25, v8
	v_max3_f32 v1, v1, v10, v11
	v_cndmask_b32_e64 v29, v29, v207, s[60:61]
	v_max3_f32 v0, v0, v9, v28
	v_max3_f32 v1, v1, v30, v31
	v_max3_f32 v0, v0, v29, v12
	v_max3_f32 v1, v1, v14, v15
	v_max3_f32 v0, v0, v13, v1
	ds_bpermute_b32 v1, v193, v0
	s_waitcnt lgkmcnt(0)
	v_max_f32_e32 v1, v1, v1
	v_max_f32_e32 v0, v0, v1
	v_cmp_lt_f32_e32 vcc, s7, v0
	s_cbranch_vccz .LBB0_902
; template <int NDVB, bool HAS_NEXT> DI void softmax_def(f32x16& sa0, f32x16& sa1, f32x16& sb0, f32x16& sb1, f32x16 (&O)[NDVB], float& muse, float& l, bool first, bf16x8 (&P)[4], bool check = true) {
;     ...
;   if (check && (first || __any(mx > 8.f))) {
;     float dl = first ? mx : fmaxf(mx, 0.f);
;     if (mx < -1e29f) dl = 0.f;
;     const float alpha = __builtin_amdgcn_exp2f(-dl);
;     muse += dl; l *= alpha;
; #pragma unroll
;     for (int i = 0; i < 16; ++i) { sa0[i] -= dl; sa1[i] -= dl; }
;     if (HAS_NEXT) {
; #pragma unroll
;       for (int i = 0; i < 16; ++i) { sb0[i] -= dl; sb1[i] -= dl; }
;     }
; #pragma unroll
;     for (int d = 0; d < NDVB; ++d)
; #pragma unroll
;       for (int i = 0; i < 16; ++i) O[d][i] *= alpha;
;   }
	v_max_f32_e32 v1, v0, v0
	v_max_f32_e32 v1, 0, v1
	v_cmp_ngt_f32_e32 vcc, s85, v0
	s_nop 1
	v_cndmask_b32_e32 v121, 0, v1, vcc
	v_exp_f32_e64 v122, -v121
	v_pk_add_f32 v[0:1], v[48:49], v[120:121]
	v_pk_mul_f32 v[78:79], v[78:79], v[122:123] op_sel_hi:[1,0]
	v_mov_b32_e32 v0, v121
	v_pk_add_f32 v[50:51], v[50:51], v[0:1] op_sel_hi:[1,0] neg_lo:[0,1] neg_hi:[0,1]
	v_pk_add_f32 v[16:17], v[16:17], v[0:1] op_sel_hi:[1,0] neg_lo:[0,1] neg_hi:[0,1]
	v_pk_add_f32 v[18:19], v[18:19], v[0:1] op_sel_hi:[1,0] neg_lo:[0,1] neg_hi:[0,1]
	v_pk_add_f32 v[2:3], v[2:3], v[0:1] op_sel_hi:[1,0] neg_lo:[0,1] neg_hi:[0,1]
	v_pk_add_f32 v[20:21], v[20:21], v[0:1] op_sel_hi:[1,0] neg_lo:[0,1] neg_hi:[0,1]
	v_pk_add_f32 v[4:5], v[4:5], v[0:1] op_sel_hi:[1,0] neg_lo:[0,1] neg_hi:[0,1]
	v_pk_add_f32 v[22:23], v[22:23], v[0:1] op_sel_hi:[1,0] neg_lo:[0,1] neg_hi:[0,1]
	v_pk_add_f32 v[6:7], v[6:7], v[0:1] op_sel_hi:[1,0] neg_lo:[0,1] neg_hi:[0,1]
	v_pk_add_f32 v[24:25], v[24:25], v[0:1] op_sel_hi:[1,0] neg_lo:[0,1] neg_hi:[0,1]
	v_pk_add_f32 v[8:9], v[8:9], v[0:1] op_sel_hi:[1,0] neg_lo:[0,1] neg_hi:[0,1]
	v_pk_add_f32 v[26:27], v[26:27], v[0:1] op_sel_hi:[1,0] neg_lo:[0,1] neg_hi:[0,1]
	v_pk_add_f32 v[10:11], v[10:11], v[0:1] op_sel_hi:[1,0] neg_lo:[0,1] neg_hi:[0,1]
	v_pk_add_f32 v[28:29], v[28:29], v[0:1] op_sel_hi:[1,0] neg_lo:[0,1] neg_hi:[0,1]
	v_pk_add_f32 v[12:13], v[12:13], v[0:1] op_sel_hi:[1,0] neg_lo:[0,1] neg_hi:[0,1]
	v_pk_add_f32 v[30:31], v[30:31], v[0:1] op_sel_hi:[1,0] neg_lo:[0,1] neg_hi:[0,1]
	v_pk_add_f32 v[14:15], v[14:15], v[0:1] op_sel_hi:[1,0] neg_lo:[0,1] neg_hi:[0,1]
	v_pk_mul_f32 v[76:77], v[76:77], v[122:123] op_sel_hi:[1,0]
	v_pk_mul_f32 v[74:75], v[74:75], v[122:123] op_sel_hi:[1,0]
	v_pk_mul_f32 v[72:73], v[72:73], v[122:123] op_sel_hi:[1,0]
	v_pk_mul_f32 v[70:71], v[70:71], v[122:123] op_sel_hi:[1,0]
	v_pk_mul_f32 v[68:69], v[68:69], v[122:123] op_sel_hi:[1,0]
	v_pk_mul_f32 v[66:67], v[66:67], v[122:123] op_sel_hi:[1,0]
	v_pk_mul_f32 v[64:65], v[64:65], v[122:123] op_sel_hi:[1,0]
	v_pk_mul_f32 v[94:95], v[94:95], v[122:123] op_sel_hi:[1,0]
	v_pk_mul_f32 v[92:93], v[92:93], v[122:123] op_sel_hi:[1,0]
	v_pk_mul_f32 v[90:91], v[90:91], v[122:123] op_sel_hi:[1,0]
	v_pk_mul_f32 v[88:89], v[88:89], v[122:123] op_sel_hi:[1,0]
	v_pk_mul_f32 v[86:87], v[86:87], v[122:123] op_sel_hi:[1,0]
	v_pk_mul_f32 v[84:85], v[84:85], v[122:123] op_sel_hi:[1,0]
	v_pk_mul_f32 v[82:83], v[82:83], v[122:123] op_sel_hi:[1,0]
	v_pk_mul_f32 v[80:81], v[80:81], v[122:123] op_sel_hi:[1,0]
	v_mul_f32_e32 v48, v48, v122
	s_branch .LBB0_903

; template <int NDVB, bool HAS_NEXT> DI void softmax_def(f32x16& sa0, f32x16& sa1, f32x16& sb0, f32x16& sb1, f32x16 (&O)[NDVB], float& muse, float& l, bool first, bf16x8 (&P)[4], bool check = true) {
;     ...
;   float sum = 0.f;
; #pragma unroll
;   for (int i = 0; i < 16; ++i) { sa0[i] = __builtin_amdgcn_exp2f(sa0[i]); sum += sa0[i]; }
; #pragma unroll
;   for (int i = 0; i < 16; ++i) { sa1[i] = __builtin_amdgcn_exp2f(sa1[i]); sum += sa1[i]; }
;   l += sum;
; template <int MODE>
; DI void nsa_branch(lds8* lds, const bf16_t* kg, const bf16_t* vg, int pitch, unsigned tiles, const bf16x8 (&q)[4], int qpos, unsigned mybits, int blk,
;                    f32x16 (&O)[2], float& muse, float& l, int tid, int lane, int grp, CmpCap& cap) {
;     ...
;   for (int t = 0; t < ntl; ++t) {
;     NS_STEP(kra, vra, 0);
;     ++t; if (t >= ntl) break;
;     NS_STEP(kra, vra, 1);
.LBB0_936:
	v_add_f32_e32 v112, v113, v112
	v_add_f32_e32 v112, v114, v112
	v_add_f32_e32 v112, v115, v112
	v_add_f32_e32 v112, v116, v112
	v_add_f32_e32 v112, v117, v112
	v_add_f32_e32 v112, v118, v112
	v_add_f32_e32 v112, v119, v112
	v_add_f32_e32 v112, v120, v112
	v_add_f32_e32 v112, v121, v112
	v_add_f32_e32 v112, v122, v112
	v_add_f32_e32 v112, v123, v112
	v_add_f32_e32 v112, v124, v112
	v_add_f32_e32 v112, v125, v112
	v_add_f32_e32 v112, v126, v112
	v_add_f32_e32 v112, v127, v112
	v_add_f32_e32 v96, v96, v112
	v_add_f32_e32 v96, v97, v96
	v_add_f32_e32 v96, v98, v96
	v_add_f32_e32 v96, v99, v96
	v_add_f32_e32 v96, v100, v96
	v_add_f32_e32 v96, v101, v96
	v_add_f32_e32 v96, v102, v96
	v_add_f32_e32 v96, v103, v96
	v_add_f32_e32 v96, v104, v96
	v_add_f32_e32 v96, v105, v96
	v_add_f32_e32 v96, v106, v96
	v_add_f32_e32 v96, v107, v96
	v_add_f32_e32 v96, v108, v96
	s_add_i32 s82, s6, 1
	v_add_f32_e32 v96, v109, v96
	s_cmp_lg_u32 s6, 2
	v_add_f32_e32 v96, v110, v96
	s_cselect_b32 s6, s82, 0
	s_add_i32 s89, s89, 2
	s_add_i32 s90, s90, 8
	v_add_f32_e32 v96, v111, v96
	s_cmp_ge_u32 s91, s88
	v_add_f32_e32 v219, v140, v96
	s_waitcnt lgkmcnt(0)
	s_barrier
	s_mov_b64 s[82:83], 0
	s_cselect_b64 s[84:85], -1, 0

; template <int MODE, int SLOT> DI void ns_valu(volatile LAS int* jl, int t, int ntl, int qpos, int h, int blk, f32x16& s0, f32x16& s1, f32x16& du0, f32x16& du1, f32x16 (&O)[2], float& muse, float& l, bf16x8 (&P)[4], CmpCap& cap) {
;     ...
;       } else if (MODE == 1) {
;         if (j == blk) {
;           const int lim = qpos - 64 * j - 4 * h;
; #pragma unroll
;           for (int i = 0; i < 16; ++i) { const int ci = (i & 3) + 8 * (i >> 2); if (ci > lim) s0[i] = NEG; if (ci + 32 > lim) s1[i] = NEG; }
;         }
.LBB0_940:
	s_mul_i32 s94, s6, 0x4800
	s_add_i32 s95, s94, 0
	v_mov_b32_e32 v139, s90
	v_add_u32_e32 v33, s95, v213
	ds_read_b32 v32, v139
	ds_read_b128 v[96:99], v33 offset:4608
	ds_read_b128 v[100:103], v33
	ds_read_b128 v[104:107], v33 offset:32
	ds_read_b128 v[108:111], v33 offset:4640
	ds_read_b128 v[112:115], v33 offset:64
	ds_read_b128 v[116:119], v33 offset:4672
	ds_read_b128 v[120:123], v33 offset:96
	ds_read_b128 v[124:127], v33 offset:4704
	s_waitcnt lgkmcnt(8)
	v_readfirstlane_b32 s84, v32
	s_nop 1
	v_lshrrev_b32_e32 v32, s84, v137
	v_and_b32_e32 v32, 1, v32
	v_cmp_eq_u32_e32 vcc, 1, v32
	s_nop 1
	v_cndmask_b32_e64 v32, v207, -v138, vcc
	v_mov_b32_e32 v33, v32
	v_mov_b64_e32 v[34:35], v[32:33]
	v_mov_b64_e32 v[36:37], v[32:33]
	v_mov_b64_e32 v[38:39], v[32:33]
	v_mov_b64_e32 v[40:41], v[32:33]
	v_mov_b64_e32 v[42:43], v[32:33]
	v_mov_b64_e32 v[44:45], v[32:33]
	v_mov_b64_e32 v[46:47], v[32:33]
	s_setprio 1
	s_waitcnt lgkmcnt(6)
	v_mfma_f32_32x32x16_bf16 v[48:63], v[100:103], v[160:163], v[32:47]
	v_mfma_f32_32x32x16_bf16 v[32:47], v[96:99], v[160:163], v[32:47]
	s_waitcnt lgkmcnt(5)
	v_mfma_f32_32x32x16_bf16 v[48:63], v[104:107], v[168:171], v[48:63]
	s_waitcnt lgkmcnt(4)
	v_mfma_f32_32x32x16_bf16 v[32:47], v[108:111], v[168:171], v[32:47]
	s_waitcnt lgkmcnt(3)
	v_mfma_f32_32x32x16_bf16 v[48:63], v[112:115], v[164:167], v[48:63]
	s_waitcnt lgkmcnt(2)
	v_mfma_f32_32x32x16_bf16 v[32:47], v[116:119], v[164:167], v[32:47]
	s_waitcnt lgkmcnt(1)
	v_mfma_f32_32x32x16_bf16 v[48:63], v[120:123], v[172:175], v[48:63]
	s_waitcnt lgkmcnt(0)
	v_mfma_f32_32x32x16_bf16 v[32:47], v[124:127], v[172:175], v[32:47]
	s_setprio 0
	ds_read_b32 v96, v139
	s_waitcnt lgkmcnt(0)
	v_readfirstlane_b32 s84, v96
	s_cmp_lg_u32 s84, s77
	s_cbranch_scc1 .LBB0_944
	s_and_b64 vcc, s[70:71], s[66:67]
	s_nop 4
	v_cndmask_b32_e32 v45, v45, v207, vcc
	s_and_b64 vcc, vcc, s[62:63]
	v_cndmask_b32_e32 v44, v44, v207, vcc
	s_and_b64 vcc, vcc, s[58:59]
	v_cndmask_b32_e32 v43, v43, v207, vcc
	s_and_b64 vcc, vcc, s[54:55]
	v_cndmask_b32_e32 v42, v42, v207, vcc
	s_and_b64 vcc, vcc, s[50:51]
	v_cndmask_b32_e32 v41, v41, v207, vcc
	s_and_b64 vcc, vcc, s[46:47]
	v_cndmask_b32_e32 v40, v40, v207, vcc
	s_and_b64 vcc, vcc, s[42:43]
	v_cndmask_b32_e32 v39, v39, v207, vcc
	s_and_b64 vcc, vcc, s[38:39]
	v_cndmask_b32_e32 v38, v38, v207, vcc
	s_and_b64 vcc, vcc, s[34:35]
	v_cndmask_b32_e32 v37, v37, v207, vcc
	s_and_b64 vcc, vcc, s[28:29]
	v_cndmask_b32_e32 v36, v36, v207, vcc
	s_and_b64 vcc, vcc, s[24:25]
	v_cndmask_b32_e32 v35, v35, v207, vcc
	s_and_b64 vcc, vcc, s[20:21]
	v_cndmask_b32_e32 v34, v34, v207, vcc
	s_and_b64 vcc, vcc, s[16:17]
	v_cndmask_b32_e32 v33, v33, v207, vcc
	s_and_b64 vcc, vcc, s[12:13]
	v_cndmask_b32_e64 v46, v46, v207, s[70:71]
	v_cndmask_b32_e32 v32, v32, v207, vcc
	s_and_saveexec_b64 s[84:85], s[74:75]
	s_mov_b32 s86, 0xf149f2ca
	v_mov_b32_e32 v47, s86
	s_or_b64 exec, exec, s[84:85]
	s_and_b64 vcc, s[72:73], s[68:69]
	v_cndmask_b32_e32 v62, v62, v207, vcc
	s_and_b64 vcc, vcc, s[64:65]
	v_cndmask_b32_e32 v61, v61, v207, vcc
	s_and_b64 vcc, vcc, s[60:61]
	v_cndmask_b32_e32 v60, v60, v207, vcc
	s_and_b64 vcc, vcc, s[56:57]
	v_cndmask_b32_e32 v59, v59, v207, vcc
	s_and_b64 vcc, vcc, s[52:53]
	v_cndmask_b32_e32 v58, v58, v207, vcc
	s_and_b64 vcc, vcc, s[48:49]
	v_cndmask_b32_e32 v57, v57, v207, vcc
	s_and_b64 vcc, vcc, s[44:45]
	v_cndmask_b32_e32 v56, v56, v207, vcc
	s_and_b64 vcc, vcc, s[40:41]
	v_cndmask_b32_e32 v55, v55, v207, vcc
	s_and_b64 vcc, vcc, s[36:37]
	v_cndmask_b32_e32 v54, v54, v207, vcc
	s_and_b64 vcc, vcc, s[30:31]
	v_cndmask_b32_e32 v53, v53, v207, vcc
	s_and_b64 vcc, vcc, s[26:27]
	v_cndmask_b32_e32 v52, v52, v207, vcc
	s_and_b64 vcc, vcc, s[22:23]
	v_cndmask_b32_e32 v51, v51, v207, vcc
	s_and_b64 vcc, vcc, s[18:19]
	v_cndmask_b32_e32 v50, v50, v207, vcc
	s_and_b64 vcc, vcc, s[14:15]
	v_cndmask_b32_e32 v49, v49, v207, vcc
	s_and_b64 vcc, vcc, s[10:11]
	v_cndmask_b32_e64 v63, v63, v207, s[72:73]
	v_cndmask_b32_e32 v48, v48, v207, vcc

; #define NS_GLOAD(k_, KR, VR) do { const int jj = __builtin_amdgcn_readfirstlane(jl[(k_)]); KR = *(const u32x4*)(kg + (size_t)(64 * jj + sr) * pitch + sc * 8); VR = *(const u32x4*)(vg + (size_t)(64 * jj + sr) * pitch + sc * 8); } while (0)
; #define NS_LSTORE(st_, KR, VR) do { lds8* b = lds + (st_) * NS_STAGE; *(LAS u32x4*)(b + sr * NS_STR + sc * 16) = KR; *(LAS u32x4*)(b + 64 * NS_STR + sr * NS_STR + sc * 16) = VR; } while (0)
; template <int MODE, int SLOT> DI void ns_valu(volatile LAS int* jl, int t, int ntl, int qpos, int h, int blk, f32x16& s0, f32x16& s1, f32x16& du0, f32x16& du1, f32x16 (&O)[2], float& muse, float& l, bf16x8 (&P)[4], CmpCap& cap) {
;     ...
;       } else if (MODE == 1) {
;         if (j == blk) {
;           const int lim = qpos - 64 * j - 4 * h;
; #pragma unroll
;           for (int i = 0; i < 16; ++i) { const int ci = (i & 3) + 8 * (i >> 2); if (ci > lim) s0[i] = NEG; if (ci + 32 > lim) s1[i] = NEG; }
;         }
; template <int MODE>
; DI void nsa_branch(lds8* lds, const bf16_t* kg, const bf16_t* vg, int pitch, unsigned tiles, const bf16x8 (&q)[4], int qpos, unsigned mybits, int blk,
;                    f32x16 (&O)[2], float& muse, float& l, int tid, int lane, int grp, CmpCap& cap) {
;     ...
;   NS_GLOAD(0, kra, vra); NS_LSTORE(0, kra, vra);
;   if (ntl > 1) { NS_GLOAD(1, kra, vra); NS_LSTORE(1, kra, vra); }
;   __syncthreads();
;   f32x16 s0, s1, du0, du1; bf16x8 P[4];
;   int st_cur = 0;
;     ...
;   for (int t = 0; t < ntl; ++t) {
;     NS_STEP(kra, vra, 0);
;     ++t; if (t >= ntl) break;
;     NS_STEP(kra, vra, 1);
.LBB0_953:
	v_add_f32_e32 v32, v97, v96
	v_add_f32_e32 v32, v98, v32
	v_add_f32_e32 v32, v99, v32
	v_add_f32_e32 v32, v100, v32
	v_add_f32_e32 v32, v101, v32
	v_add_f32_e32 v32, v102, v32
	v_add_f32_e32 v32, v103, v32
	v_add_f32_e32 v32, v104, v32
	v_add_f32_e32 v32, v105, v32
	v_add_f32_e32 v32, v106, v32
	v_add_f32_e32 v32, v107, v32
	v_add_f32_e32 v32, v108, v32
	v_add_f32_e32 v32, v109, v32
	v_add_f32_e32 v32, v110, v32
	v_add_f32_e32 v32, v111, v32
	v_add_f32_e32 v32, v112, v32
	v_add_f32_e32 v32, v113, v32
	v_add_f32_e32 v32, v114, v32
	v_add_f32_e32 v32, v115, v32
	v_add_f32_e32 v32, v116, v32
	v_add_f32_e32 v32, v117, v32
	v_add_f32_e32 v32, v118, v32
	v_add_f32_e32 v32, v119, v32
	v_add_f32_e32 v32, v120, v32
	v_add_f32_e32 v32, v121, v32
	v_add_f32_e32 v32, v122, v32
	v_add_f32_e32 v32, v123, v32
	v_add_f32_e32 v32, v124, v32
	v_add_f32_e32 v32, v125, v32
	v_add_f32_e32 v32, v126, v32
	v_add_f32_e32 v32, v127, v32
	s_add_i32 s84, s89, -2
	v_add_f32_e32 v139, v219, v32
	s_mov_b64 s[82:83], -1
	s_cmp_ge_u32 s84, s88
	s_mov_b64 s[84:85], -1
	s_movk_i32 s95, 0x1ff
	s_waitcnt lgkmcnt(0)
	s_barrier
	s_cbranch_scc1 .LBB0_937
	s_cmp_lt_u32 s89, s88
	s_cselect_b64 s[82:83], -1, 0
	s_cmp_ge_u32 s89, s88
	s_cbranch_scc1 .LBB0_956
	v_mov_b32_e32 v32, s90
	ds_read_b32 v32, v32 offset:12
	s_waitcnt lgkmcnt(0)
	v_readfirstlane_b32 s84, v32
	s_nop 1
	v_lshl_add_u32 v32, s84, 6, v212
	v_ashrrev_i32_e32 v33, 31, v32
	v_lshlrev_b64 v[32:33], 9, v[32:33]
	v_lshl_add_u64 v[34:35], v[194:195], 0, v[32:33]
	v_lshl_add_u64 v[32:33], v[196:197], 0, v[32:33]
	global_load_dwordx4 v[128:131], v[34:35], off
	global_load_dwordx4 v[132:135], v[32:33], off
.LBB0_956:
	s_add_i32 s84, s6, 1
	s_cmp_lg_u32 s6, 2
	s_cselect_b32 s6, s84, 0
	v_mov_b32_e32 v140, s90
	ds_read_b32 v32, v140 offset:4
	s_mul_i32 s86, s6, 0x4800
	s_add_i32 s87, s86, 0
	v_add_u32_e32 v60, s87, v213
	s_waitcnt lgkmcnt(0)
	v_readfirstlane_b32 s84, v32
	s_nop 1
	v_lshrrev_b32_e32 v32, s84, v137
	v_and_b32_e32 v32, 1, v32
	v_cmp_eq_u32_e32 vcc, 1, v32
	ds_read_b128 v[32:35], v60 offset:4608
	ds_read_b128 v[36:39], v60
	ds_read_b128 v[40:43], v60 offset:32
	ds_read_b128 v[44:47], v60 offset:4640
	ds_read_b128 v[48:51], v60 offset:64
	ds_read_b128 v[52:55], v60 offset:4672
	ds_read_b128 v[56:59], v60 offset:96
	ds_read_b128 v[60:63], v60 offset:4704
	v_cndmask_b32_e64 v96, v207, -v138, vcc
	v_mov_b32_e32 v97, v96
	v_mov_b64_e32 v[98:99], v[96:97]
	v_mov_b64_e32 v[100:101], v[96:97]
	v_mov_b64_e32 v[102:103], v[96:97]
	v_mov_b64_e32 v[104:105], v[96:97]
	v_mov_b64_e32 v[106:107], v[96:97]
	v_mov_b64_e32 v[108:109], v[96:97]
	v_mov_b64_e32 v[110:111], v[96:97]
	s_setprio 1
	s_waitcnt lgkmcnt(6)
	v_mfma_f32_32x32x16_bf16 v[112:127], v[36:39], v[160:163], v[96:111]
	v_mfma_f32_32x32x16_bf16 v[96:111], v[32:35], v[160:163], v[96:111]
	s_waitcnt lgkmcnt(5)
	v_mfma_f32_32x32x16_bf16 v[112:127], v[40:43], v[168:171], v[112:127]
	s_waitcnt lgkmcnt(4)
	v_mfma_f32_32x32x16_bf16 v[96:111], v[44:47], v[168:171], v[96:111]
	s_waitcnt lgkmcnt(3)
	v_mfma_f32_32x32x16_bf16 v[112:127], v[48:51], v[164:167], v[112:127]
	s_waitcnt lgkmcnt(2)
	v_mfma_f32_32x32x16_bf16 v[96:111], v[52:55], v[164:167], v[96:111]
	s_waitcnt lgkmcnt(1)
	v_mfma_f32_32x32x16_bf16 v[112:127], v[56:59], v[172:175], v[112:127]
	s_waitcnt lgkmcnt(0)
	v_mfma_f32_32x32x16_bf16 v[96:111], v[60:63], v[172:175], v[96:111]
	s_setprio 0
	ds_read_b32 v32, v140 offset:4
	s_waitcnt lgkmcnt(0)
	v_readfirstlane_b32 s84, v32
	s_cmp_lg_u32 s84, s77
	s_cbranch_scc1 .LBB0_960
	s_and_b64 vcc, s[70:71], s[66:67]
	s_nop 4
	v_cndmask_b32_e32 v109, v109, v207, vcc
	s_and_b64 vcc, vcc, s[62:63]
	v_cndmask_b32_e32 v108, v108, v207, vcc
	s_and_b64 vcc, vcc, s[58:59]
	v_cndmask_b32_e32 v107, v107, v207, vcc
	s_and_b64 vcc, vcc, s[54:55]
	v_cndmask_b32_e32 v106, v106, v207, vcc
	s_and_b64 vcc, vcc, s[50:51]
	v_cndmask_b32_e32 v105, v105, v207, vcc
	s_and_b64 vcc, vcc, s[46:47]
	v_cndmask_b32_e32 v104, v104, v207, vcc
	s_and_b64 vcc, vcc, s[42:43]
	v_cndmask_b32_e32 v103, v103, v207, vcc
	s_and_b64 vcc, vcc, s[38:39]
	v_cndmask_b32_e32 v102, v102, v207, vcc
	s_and_b64 vcc, vcc, s[34:35]
	v_cndmask_b32_e32 v101, v101, v207, vcc
	s_and_b64 vcc, vcc, s[28:29]
	v_cndmask_b32_e32 v100, v100, v207, vcc
	s_and_b64 vcc, vcc, s[24:25]
	v_cndmask_b32_e32 v99, v99, v207, vcc
	s_and_b64 vcc, vcc, s[20:21]
	v_cndmask_b32_e32 v98, v98, v207, vcc
	s_and_b64 vcc, vcc, s[16:17]
	v_cndmask_b32_e32 v97, v97, v207, vcc
	s_and_b64 vcc, vcc, s[12:13]
	v_cndmask_b32_e64 v110, v110, v207, s[70:71]
	v_cndmask_b32_e32 v96, v96, v207, vcc
	s_and_saveexec_b64 s[84:85], s[74:75]
	s_mov_b32 s94, 0xf149f2ca
	v_mov_b32_e32 v111, s94
	s_or_b64 exec, exec, s[84:85]
	s_and_b64 vcc, s[72:73], s[68:69]
	v_cndmask_b32_e32 v126, v126, v207, vcc
	s_and_b64 vcc, vcc, s[64:65]
	v_cndmask_b32_e32 v125, v125, v207, vcc
	s_and_b64 vcc, vcc, s[60:61]
	v_cndmask_b32_e32 v124, v124, v207, vcc
	s_and_b64 vcc, vcc, s[56:57]
	v_cndmask_b32_e32 v123, v123, v207, vcc
	s_and_b64 vcc, vcc, s[52:53]
	v_cndmask_b32_e32 v122, v122, v207, vcc
	s_and_b64 vcc, vcc, s[48:49]
	v_cndmask_b32_e32 v121, v121, v207, vcc
	s_and_b64 vcc, vcc, s[44:45]
	v_cndmask_b32_e32 v120, v120, v207, vcc
	s_and_b64 vcc, vcc, s[40:41]
	v_cndmask_b32_e32 v119, v119, v207, vcc
	s_and_b64 vcc, vcc, s[36:37]
	v_cndmask_b32_e32 v118, v118, v207, vcc
	s_and_b64 vcc, vcc, s[30:31]
	v_cndmask_b32_e32 v117, v117, v207, vcc
	s_and_b64 vcc, vcc, s[26:27]
	v_cndmask_b32_e32 v116, v116, v207, vcc
	s_and_b64 vcc, vcc, s[22:23]
	v_cndmask_b32_e32 v115, v115, v207, vcc
	s_and_b64 vcc, vcc, s[18:19]
	v_cndmask_b32_e32 v114, v114, v207, vcc
	s_and_b64 vcc, vcc, s[14:15]
	v_cndmask_b32_e32 v113, v113, v207, vcc
	s_and_b64 vcc, vcc, s[10:11]
	v_cndmask_b32_e64 v127, v127, v207, s[72:73]
	v_cndmask_b32_e32 v112, v112, v207, vcc

; template <int NDVB, bool HAS_NEXT> DI void softmax_def(f32x16& sa0, f32x16& sa1, f32x16& sb0, f32x16& sb1, f32x16 (&O)[NDVB], float& muse, float& l, bool first, bf16x8 (&P)[4], bool check = true) {
;     ...
;   float sum = 0.f;
; #pragma unroll
;   for (int i = 0; i < 16; ++i) { sa0[i] = __builtin_amdgcn_exp2f(sa0[i]); sum += sa0[i]; }
; #pragma unroll
;   for (int i = 0; i < 16; ++i) { sa1[i] = __builtin_amdgcn_exp2f(sa1[i]); sum += sa1[i]; }
;   l += sum;
; template <int MODE>
; DI void nsa_branch(lds8* lds, const bf16_t* kg, const bf16_t* vg, int pitch, unsigned tiles, const bf16x8 (&q)[4], int qpos, unsigned mybits, int blk,
;                    f32x16 (&O)[2], float& muse, float& l, int tid, int lane, int grp, CmpCap& cap) {
;     ...
;   for (int t = 0; t < ntl; ++t) {
;     NS_STEP(kra, vra, 0);
;     ++t; if (t >= ntl) break;
;     NS_STEP(kra, vra, 1);
.LBB0_979:
	v_add_f32_e32 v144, v145, v144
	v_add_f32_e32 v144, v146, v144
	v_add_f32_e32 v144, v147, v144
	v_add_f32_e32 v144, v148, v144
	v_add_f32_e32 v144, v149, v144
	v_add_f32_e32 v144, v150, v144
	v_add_f32_e32 v144, v151, v144
	v_add_f32_e32 v144, v152, v144
	v_add_f32_e32 v144, v153, v144
	v_add_f32_e32 v144, v154, v144
	v_add_f32_e32 v144, v155, v144
	v_add_f32_e32 v144, v156, v144
	v_add_f32_e32 v144, v157, v144
	v_add_f32_e32 v144, v158, v144
	v_add_f32_e32 v144, v159, v144
	v_add_f32_e32 v128, v128, v144
	v_add_f32_e32 v128, v129, v128
	v_add_f32_e32 v128, v130, v128
	v_add_f32_e32 v128, v131, v128
	v_add_f32_e32 v128, v132, v128
	v_add_f32_e32 v128, v133, v128
	v_add_f32_e32 v128, v134, v128
	v_add_f32_e32 v128, v135, v128
	v_add_f32_e32 v128, v136, v128
	v_add_f32_e32 v128, v137, v128
	v_add_f32_e32 v128, v138, v128
	v_add_f32_e32 v128, v139, v128
	v_add_f32_e32 v128, v140, v128
	s_add_i32 s8, s6, 1
	v_add_f32_e32 v128, v141, v128
	s_cmp_lg_u32 s6, 2
	v_add_f32_e32 v128, v142, v128
	s_cselect_b32 s6, s8, 0
	s_add_i32 s46, s46, 2
	s_add_i32 s0, s0, 8
	v_add_f32_e32 v128, v143, v128
	s_cmp_ge_u32 s47, s3
	v_add_f32_e32 v128, v223, v128
	s_waitcnt lgkmcnt(0)
	s_barrier
	s_mov_b64 s[8:9], 0
	s_cselect_b64 s[10:11], -1, 0

; template <int MODE, int SLOT> DI void ns_valu(volatile LAS int* jl, int t, int ntl, int qpos, int h, int blk, f32x16& s0, f32x16& s1, f32x16& du0, f32x16& du1, f32x16 (&O)[2], float& muse, float& l, bf16x8 (&P)[4], CmpCap& cap) {
;     ...
;       } else {
;         if (j == blk || j + 8 == blk) {
;           const int lim = qpos - 64 * j - 4 * h, lo = lim - 512;
; #pragma unroll
;           for (int i = 0; i < 16; ++i) { const int ci = (i & 3) + 8 * (i >> 2); if (ci > lim || ci <= lo) s0[i] = NEG; if (ci + 32 > lim || ci + 32 <= lo) s1[i] = NEG; }
;         }
.LBB0_983:
	s_mul_i32 s48, s6, 0x4800
	s_add_i32 s49, s48, 0
	v_add_u32_e32 v97, s49, v213
	ds_read_b128 v[130:133], v97
	ds_read_b128 v[134:137], v97 offset:32
	ds_read_b128 v[138:141], v97 offset:4608
	ds_read_b128 v[142:145], v97 offset:4640
	ds_read_b128 v[146:149], v97 offset:64
	ds_read_b128 v[150:153], v97 offset:96
	ds_read_b128 v[154:157], v97 offset:4672
	ds_read_b128 v[222:225], v97 offset:4704
	v_xor_b32_e32 v96, 0x80000000, v221
	v_mov_b32_e32 v97, v96
	v_mov_b64_e32 v[98:99], v[96:97]
	v_mov_b64_e32 v[100:101], v[96:97]
	v_mov_b64_e32 v[102:103], v[96:97]
	v_mov_b64_e32 v[104:105], v[96:97]
	v_mov_b64_e32 v[106:107], v[96:97]
	v_mov_b64_e32 v[108:109], v[96:97]
	v_mov_b64_e32 v[110:111], v[96:97]
	s_setprio 1
	s_waitcnt lgkmcnt(7)
	v_mfma_f32_32x32x16_bf16 v[112:127], v[130:133], v[160:163], v[96:111]
	s_waitcnt lgkmcnt(5)
	v_mfma_f32_32x32x16_bf16 v[96:111], v[138:141], v[160:163], v[96:111]
	v_mfma_f32_32x32x16_bf16 v[112:127], v[134:137], v[168:171], v[112:127]
	s_waitcnt lgkmcnt(4)
	v_mfma_f32_32x32x16_bf16 v[96:111], v[142:145], v[168:171], v[96:111]
	s_waitcnt lgkmcnt(3)
	v_mfma_f32_32x32x16_bf16 v[112:127], v[146:149], v[164:167], v[112:127]
	s_waitcnt lgkmcnt(1)
	v_mfma_f32_32x32x16_bf16 v[96:111], v[154:157], v[164:167], v[96:111]
	v_mfma_f32_32x32x16_bf16 v[112:127], v[150:153], v[172:175], v[112:127]
	s_waitcnt lgkmcnt(0)
	v_mfma_f32_32x32x16_bf16 v[96:111], v[222:225], v[172:175], v[96:111]
	s_setprio 0
	v_mov_b32_e32 v129, s0
	ds_read_b32 v129, v129
	s_waitcnt lgkmcnt(0)
	v_readfirstlane_b32 s8, v129
	s_cmp_eq_u32 s8, s77
	s_cselect_b64 s[10:11], -1, 0
	s_add_i32 s9, s8, 8
	s_cmp_eq_u32 s9, s77
	s_cselect_b64 s[12:13], -1, 0
	s_or_b64 s[10:11], s[10:11], s[12:13]
	s_andn2_b64 vcc, exec, s[10:11]
	s_cbranch_vccnz .LBB0_987
	v_lshl_or_b32 v129, s8, 6, v214
	v_sub_u32_e32 v129, v211, v129
	v_subrev_u32_e32 v130, 32, v129
	v_cmp_gt_u32_e64 s[8:9], s33, v130
	v_add_u32_e32 v130, -1, v129
	v_cmp_gt_u32_e32 vcc, s33, v129
	v_cndmask_b32_e64 v96, v207, v96, s[8:9]
	v_cmp_gt_u32_e64 s[8:9], s33, v130
	v_subrev_u32_e32 v130, 33, v129
	v_cmp_gt_u32_e64 s[10:11], s33, v130
	v_add_u32_e32 v130, -2, v129
	s_nop 0
	v_cndmask_b32_e64 v97, v207, v97, s[10:11]
	v_cmp_gt_u32_e64 s[10:11], s33, v130
	v_subrev_u32_e32 v130, 34, v129
	v_cmp_gt_u32_e64 s[12:13], s33, v130
	v_add_u32_e32 v130, -3, v129
	s_nop 0
	v_cndmask_b32_e64 v98, v207, v98, s[12:13]
	v_cmp_gt_u32_e64 s[12:13], s33, v130
	v_subrev_u32_e32 v130, 35, v129
	v_cmp_gt_u32_e64 s[14:15], s33, v130
	v_add_u32_e32 v130, -8, v129
	s_nop 0
	v_cndmask_b32_e64 v99, v207, v99, s[14:15]
	v_cmp_gt_u32_e64 s[14:15], s33, v130
	v_subrev_u32_e32 v130, 40, v129
	v_cmp_gt_u32_e64 s[16:17], s33, v130
	v_add_u32_e32 v130, -9, v129
	s_nop 0
	v_cndmask_b32_e64 v100, v207, v100, s[16:17]
	v_cmp_gt_u32_e64 s[16:17], s33, v130
	v_subrev_u32_e32 v130, 41, v129
	v_cmp_gt_u32_e64 s[18:19], s33, v130
	v_add_u32_e32 v130, -10, v129
	s_nop 0
	v_cndmask_b32_e64 v101, v207, v101, s[18:19]
	v_cmp_gt_u32_e64 s[18:19], s33, v130
	v_subrev_u32_e32 v130, 42, v129
	v_cmp_gt_u32_e64 s[20:21], s33, v130
	v_add_u32_e32 v130, -11, v129
	s_nop 0
	v_cndmask_b32_e64 v102, v207, v102, s[20:21]
	v_cmp_gt_u32_e64 s[20:21], s33, v130
	v_subrev_u32_e32 v130, 43, v129
	v_cmp_gt_u32_e64 s[22:23], s33, v130
	v_add_u32_e32 v130, -16, v129
	s_nop 0
	v_cndmask_b32_e64 v103, v207, v103, s[22:23]
	v_cmp_gt_u32_e64 s[22:23], s33, v130
	v_subrev_u32_e32 v130, 48, v129
	v_cmp_gt_u32_e64 s[24:25], s33, v130
	v_subrev_u32_e32 v130, 17, v129
	s_nop 0
	v_cndmask_b32_e64 v104, v207, v104, s[24:25]
	v_cmp_gt_u32_e64 s[24:25], s33, v130
	v_subrev_u32_e32 v130, 49, v129
	v_cmp_gt_u32_e64 s[26:27], s33, v130
	v_subrev_u32_e32 v130, 18, v129
	s_nop 0
	v_cndmask_b32_e64 v105, v207, v105, s[26:27]
	v_cmp_gt_u32_e64 s[26:27], s33, v130
	v_subrev_u32_e32 v130, 50, v129
	v_cmp_gt_u32_e64 s[28:29], s33, v130
	v_subrev_u32_e32 v130, 19, v129
	s_nop 0
	v_cndmask_b32_e64 v106, v207, v106, s[28:29]
	v_cmp_gt_u32_e64 s[28:29], s33, v130
	v_subrev_u32_e32 v130, 51, v129
	v_cmp_gt_u32_e64 s[30:31], s33, v130
	v_subrev_u32_e32 v130, 24, v129
	s_nop 0
	v_cndmask_b32_e64 v107, v207, v107, s[30:31]
	v_cmp_gt_u32_e64 s[30:31], s33, v130
	v_subrev_u32_e32 v130, 56, v129
	v_cmp_gt_u32_e64 s[34:35], s33, v130
	v_subrev_u32_e32 v130, 25, v129
	s_nop 0
	v_cndmask_b32_e64 v108, v207, v108, s[34:35]
	v_cmp_gt_u32_e64 s[34:35], s33, v130
	v_subrev_u32_e32 v130, 57, v129
	v_cmp_gt_u32_e64 s[36:37], s33, v130
	v_subrev_u32_e32 v130, 26, v129
	s_nop 0
	v_cndmask_b32_e64 v109, v207, v109, s[36:37]
	v_cmp_gt_u32_e64 s[36:37], s33, v130
	v_subrev_u32_e32 v130, 58, v129
	v_cmp_gt_u32_e64 s[38:39], s33, v130
	v_subrev_u32_e32 v130, 27, v129
	v_subrev_u32_e32 v129, 59, v129
	v_cndmask_b32_e64 v110, v207, v110, s[38:39]
	v_cmp_gt_u32_e64 s[38:39], s33, v130
	v_cmp_lt_u32_e64 s[40:41], s95, v129
	s_and_saveexec_b64 s[44:45], s[40:41]
	s_mov_b32 s1, 0xf149f2ca
	v_mov_b32_e32 v111, s1
	s_or_b64 exec, exec, s[44:45]
	v_cndmask_b32_e32 v112, v207, v112, vcc
	v_cndmask_b32_e64 v113, v207, v113, s[8:9]
	v_cndmask_b32_e64 v114, v207, v114, s[10:11]
	v_cndmask_b32_e64 v115, v207, v115, s[12:13]
	v_cndmask_b32_e64 v116, v207, v116, s[14:15]
	v_cndmask_b32_e64 v117, v207, v117, s[16:17]
	v_cndmask_b32_e64 v118, v207, v118, s[18:19]
	v_cndmask_b32_e64 v119, v207, v119, s[20:21]
	v_cndmask_b32_e64 v120, v207, v120, s[22:23]
	v_cndmask_b32_e64 v121, v207, v121, s[24:25]
	v_cndmask_b32_e64 v122, v207, v122, s[26:27]
	v_cndmask_b32_e64 v123, v207, v123, s[28:29]
	v_cndmask_b32_e64 v124, v207, v124, s[30:31]
	v_cndmask_b32_e64 v125, v207, v125, s[34:35]
	v_cndmask_b32_e64 v126, v207, v126, s[36:37]
	v_cndmask_b32_e64 v127, v207, v127, s[38:39]

; #define NS_GLOAD(k_, KR, VR) do { const int jj = __builtin_amdgcn_readfirstlane(jl[(k_)]); KR = *(const u32x4*)(kg + (size_t)(64 * jj + sr) * pitch + sc * 8); VR = *(const u32x4*)(vg + (size_t)(64 * jj + sr) * pitch + sc * 8); } while (0)
; #define NS_LSTORE(st_, KR, VR) do { lds8* b = lds + (st_) * NS_STAGE; *(LAS u32x4*)(b + sr * NS_STR + sc * 16) = KR; *(LAS u32x4*)(b + 64 * NS_STR + sr * NS_STR + sc * 16) = VR; } while (0)
; template <int NDVB, bool HAS_NEXT> DI void softmax_def(f32x16& sa0, f32x16& sa1, f32x16& sb0, f32x16& sb1, f32x16 (&O)[NDVB], float& muse, float& l, bool first, bf16x8 (&P)[4], bool check = true) {
;     ...
;   float sum = 0.f;
; #pragma unroll
;   for (int i = 0; i < 16; ++i) { sa0[i] = __builtin_amdgcn_exp2f(sa0[i]); sum += sa0[i]; }
; #pragma unroll
;   for (int i = 0; i < 16; ++i) { sa1[i] = __builtin_amdgcn_exp2f(sa1[i]); sum += sa1[i]; }
;   l += sum;
; template <int MODE>
; DI void nsa_branch(lds8* lds, const bf16_t* kg, const bf16_t* vg, int pitch, unsigned tiles, const bf16x8 (&q)[4], int qpos, unsigned mybits, int blk,
;                    f32x16 (&O)[2], float& muse, float& l, int tid, int lane, int grp, CmpCap& cap) {
;     ...
;   NS_GLOAD(0, kra, vra); NS_LSTORE(0, kra, vra);
;   if (ntl > 1) { NS_GLOAD(1, kra, vra); NS_LSTORE(1, kra, vra); }
;   __syncthreads();
;   f32x16 s0, s1, du0, du1; bf16x8 P[4];
;   int st_cur = 0;
.LBB0_996:
	v_add_f32_e32 v96, v130, v129
	v_add_f32_e32 v96, v131, v96
	v_add_f32_e32 v96, v132, v96
	v_add_f32_e32 v96, v133, v96
	v_add_f32_e32 v96, v134, v96
	v_add_f32_e32 v96, v135, v96
	v_add_f32_e32 v96, v136, v96
	v_add_f32_e32 v96, v137, v96
	v_add_f32_e32 v96, v138, v96
	v_add_f32_e32 v96, v139, v96
	v_add_f32_e32 v96, v140, v96
	v_add_f32_e32 v96, v141, v96
	v_add_f32_e32 v96, v142, v96
	v_add_f32_e32 v96, v143, v96
	v_add_f32_e32 v96, v144, v96
	v_add_f32_e32 v96, v145, v96
	v_add_f32_e32 v96, v146, v96
	v_add_f32_e32 v96, v147, v96
	v_add_f32_e32 v96, v148, v96
	v_add_f32_e32 v96, v149, v96
	v_add_f32_e32 v96, v150, v96
	v_add_f32_e32 v96, v151, v96
	v_add_f32_e32 v96, v152, v96
	v_add_f32_e32 v96, v153, v96
	v_add_f32_e32 v96, v154, v96
	v_add_f32_e32 v96, v155, v96
	v_add_f32_e32 v96, v156, v96
	v_add_f32_e32 v96, v157, v96
	v_add_f32_e32 v96, v158, v96
	v_add_f32_e32 v96, v159, v96
	v_add_f32_e32 v96, v222, v96
	s_add_i32 s10, s46, -2
	v_add_f32_e32 v222, v128, v96
	s_mov_b64 s[8:9], -1
	s_cmp_ge_u32 s10, s3
	s_mov_b64 s[10:11], -1
	s_waitcnt lgkmcnt(0)
	s_barrier
	s_cbranch_scc1 .LBB0_980
	s_cmp_lt_u32 s46, s3
	s_cselect_b64 s[42:43], -1, 0
	s_cmp_ge_u32 s46, s3
	s_cbranch_scc1 .LBB0_999
	v_mov_b32_e32 v96, s0
	ds_read_b32 v96, v96 offset:12
	s_waitcnt lgkmcnt(0)
	v_readfirstlane_b32 s8, v96
	s_nop 1
	v_lshl_add_u32 v96, s8, 6, v212
	v_ashrrev_i32_e32 v97, 31, v96
	v_lshlrev_b64 v[96:97], 9, v[96:97]
	v_lshl_add_u64 v[98:99], v[194:195], 0, v[96:97]
	v_lshl_add_u64 v[96:97], v[196:197], 0, v[96:97]
	global_load_dwordx4 v[176:179], v[98:99], off offset:256
	global_load_dwordx4 v[180:183], v[96:97], off offset:256
; template <int MODE, int SLOT> DI void ns_valu(volatile LAS int* jl, int t, int ntl, int qpos, int h, int blk, f32x16& s0, f32x16& s1, f32x16& du0, f32x16& du1, f32x16 (&O)[2], float& muse, float& l, bf16x8 (&P)[4], CmpCap& cap) {
;     ...
;       } else {
;         if (j == blk || j + 8 == blk) {
;           const int lim = qpos - 64 * j - 4 * h, lo = lim - 512;
; #pragma unroll
;           for (int i = 0; i < 16; ++i) { const int ci = (i & 3) + 8 * (i >> 2); if (ci > lim || ci <= lo) s0[i] = NEG; if (ci + 32 > lim || ci + 32 <= lo) s1[i] = NEG; }
;         }
; template <int MODE>
; DI void nsa_branch(lds8* lds, const bf16_t* kg, const bf16_t* vg, int pitch, unsigned tiles, const bf16x8 (&q)[4], int qpos, unsigned mybits, int blk,
;                    f32x16 (&O)[2], float& muse, float& l, int tid, int lane, int grp, CmpCap& cap) {
;     ...
;   for (int t = 0; t < ntl; ++t) {
;     NS_STEP(kra, vra, 0);
.LBB0_999:
	s_add_i32 s8, s6, 1
	s_cmp_lg_u32 s6, 2
	s_cselect_b32 s6, s8, 0
	s_mul_i32 s48, s6, 0x4800
	s_add_i32 s49, s48, 0
	v_add_u32_e32 v124, s49, v213
	ds_read_b128 v[96:99], v124
	ds_read_b128 v[100:103], v124 offset:32
	ds_read_b128 v[104:107], v124 offset:4608
	ds_read_b128 v[108:111], v124 offset:4640
	ds_read_b128 v[112:115], v124 offset:64
	ds_read_b128 v[116:119], v124 offset:96
	ds_read_b128 v[120:123], v124 offset:4672
	ds_read_b128 v[124:127], v124 offset:4704
	v_xor_b32_e32 v128, 0x80000000, v221
	v_mov_b32_e32 v129, v128
	v_mov_b64_e32 v[130:131], v[128:129]
	v_mov_b64_e32 v[132:133], v[128:129]
	v_mov_b64_e32 v[134:135], v[128:129]
	v_mov_b64_e32 v[136:137], v[128:129]
	v_mov_b64_e32 v[138:139], v[128:129]
	v_mov_b64_e32 v[140:141], v[128:129]
	v_mov_b64_e32 v[142:143], v[128:129]
	s_setprio 1
	s_waitcnt lgkmcnt(7)
	v_mfma_f32_32x32x16_bf16 v[144:159], v[96:99], v[160:163], v[128:143]
	s_waitcnt lgkmcnt(5)
	v_mfma_f32_32x32x16_bf16 v[128:143], v[104:107], v[160:163], v[128:143]
	v_mfma_f32_32x32x16_bf16 v[144:159], v[100:103], v[168:171], v[144:159]
	s_waitcnt lgkmcnt(4)
	v_mfma_f32_32x32x16_bf16 v[128:143], v[108:111], v[168:171], v[128:143]
	s_waitcnt lgkmcnt(3)
	v_mfma_f32_32x32x16_bf16 v[144:159], v[112:115], v[164:167], v[144:159]
	s_waitcnt lgkmcnt(1)
	v_mfma_f32_32x32x16_bf16 v[128:143], v[120:123], v[164:167], v[128:143]
	v_mfma_f32_32x32x16_bf16 v[144:159], v[116:119], v[172:175], v[144:159]
	s_waitcnt lgkmcnt(0)
	v_mfma_f32_32x32x16_bf16 v[128:143], v[124:127], v[172:175], v[128:143]
	s_setprio 0
	v_mov_b32_e32 v96, s0
	ds_read_b32 v96, v96 offset:4
	s_waitcnt lgkmcnt(0)
	v_readfirstlane_b32 s8, v96
	s_cmp_eq_u32 s8, s77
	s_cselect_b64 s[10:11], -1, 0
	s_add_i32 s9, s8, 8
	s_cmp_eq_u32 s9, s77
	s_cselect_b64 s[12:13], -1, 0
	s_or_b64 s[10:11], s[10:11], s[12:13]
	s_andn2_b64 vcc, exec, s[10:11]
	s_cbranch_vccnz .LBB0_1003
	v_lshl_or_b32 v96, s8, 6, v214
	v_sub_u32_e32 v96, v211, v96
	v_subrev_u32_e32 v97, 32, v96
	v_cmp_gt_u32_e64 s[8:9], s33, v97
	v_add_u32_e32 v97, -1, v96
	v_cmp_gt_u32_e32 vcc, s33, v96
	v_cndmask_b32_e64 v128, v207, v128, s[8:9]
	v_cmp_gt_u32_e64 s[8:9], s33, v97
	v_subrev_u32_e32 v97, 33, v96
	v_cmp_gt_u32_e64 s[10:11], s33, v97
	v_add_u32_e32 v97, -2, v96
	s_nop 0
	v_cndmask_b32_e64 v129, v207, v129, s[10:11]
	v_cmp_gt_u32_e64 s[10:11], s33, v97
	v_subrev_u32_e32 v97, 34, v96
	v_cmp_gt_u32_e64 s[12:13], s33, v97
	v_add_u32_e32 v97, -3, v96
	s_nop 0
	v_cndmask_b32_e64 v130, v207, v130, s[12:13]
	v_cmp_gt_u32_e64 s[12:13], s33, v97
	v_subrev_u32_e32 v97, 35, v96
	v_cmp_gt_u32_e64 s[14:15], s33, v97
	v_add_u32_e32 v97, -8, v96
	s_nop 0
	v_cndmask_b32_e64 v131, v207, v131, s[14:15]
	v_cmp_gt_u32_e64 s[14:15], s33, v97
	v_subrev_u32_e32 v97, 40, v96
	v_cmp_gt_u32_e64 s[16:17], s33, v97
	v_add_u32_e32 v97, -9, v96
	s_nop 0
	v_cndmask_b32_e64 v132, v207, v132, s[16:17]
	v_cmp_gt_u32_e64 s[16:17], s33, v97
	v_subrev_u32_e32 v97, 41, v96
	v_cmp_gt_u32_e64 s[18:19], s33, v97
	v_add_u32_e32 v97, -10, v96
	s_nop 0
	v_cndmask_b32_e64 v133, v207, v133, s[18:19]
	v_cmp_gt_u32_e64 s[18:19], s33, v97
	v_subrev_u32_e32 v97, 42, v96
	v_cmp_gt_u32_e64 s[20:21], s33, v97
	v_add_u32_e32 v97, -11, v96
	s_nop 0
	v_cndmask_b32_e64 v134, v207, v134, s[20:21]
	v_cmp_gt_u32_e64 s[20:21], s33, v97
	v_subrev_u32_e32 v97, 43, v96
	v_cmp_gt_u32_e64 s[22:23], s33, v97
	v_add_u32_e32 v97, -16, v96
	s_nop 0
	v_cndmask_b32_e64 v135, v207, v135, s[22:23]
	v_cmp_gt_u32_e64 s[22:23], s33, v97
	v_subrev_u32_e32 v97, 48, v96
	v_cmp_gt_u32_e64 s[24:25], s33, v97
	v_subrev_u32_e32 v97, 17, v96
	s_nop 0
	v_cndmask_b32_e64 v136, v207, v136, s[24:25]
	v_cmp_gt_u32_e64 s[24:25], s33, v97
	v_subrev_u32_e32 v97, 49, v96
	v_cmp_gt_u32_e64 s[26:27], s33, v97
	v_subrev_u32_e32 v97, 18, v96
	s_nop 0
	v_cndmask_b32_e64 v137, v207, v137, s[26:27]
	v_cmp_gt_u32_e64 s[26:27], s33, v97
	v_subrev_u32_e32 v97, 50, v96
	v_cmp_gt_u32_e64 s[28:29], s33, v97
	v_subrev_u32_e32 v97, 19, v96
	s_nop 0
	v_cndmask_b32_e64 v138, v207, v138, s[28:29]
	v_cmp_gt_u32_e64 s[28:29], s33, v97
	v_subrev_u32_e32 v97, 51, v96
	v_cmp_gt_u32_e64 s[30:31], s33, v97
	v_subrev_u32_e32 v97, 24, v96
	s_nop 0
	v_cndmask_b32_e64 v139, v207, v139, s[30:31]
	v_cmp_gt_u32_e64 s[30:31], s33, v97
	v_subrev_u32_e32 v97, 56, v96
	v_cmp_gt_u32_e64 s[34:35], s33, v97
	v_subrev_u32_e32 v97, 25, v96
	s_nop 0
	v_cndmask_b32_e64 v140, v207, v140, s[34:35]
	v_cmp_gt_u32_e64 s[34:35], s33, v97
	v_subrev_u32_e32 v97, 57, v96
	v_cmp_gt_u32_e64 s[36:37], s33, v97
	v_subrev_u32_e32 v97, 26, v96
	s_nop 0
	v_cndmask_b32_e64 v141, v207, v141, s[36:37]
	v_cmp_gt_u32_e64 s[36:37], s33, v97
	v_subrev_u32_e32 v97, 58, v96
	v_cmp_gt_u32_e64 s[38:39], s33, v97
	v_subrev_u32_e32 v97, 27, v96
	v_subrev_u32_e32 v96, 59, v96
	v_cndmask_b32_e64 v142, v207, v142, s[38:39]
	v_cmp_gt_u32_e64 s[38:39], s33, v97
	v_cmp_lt_u32_e64 s[40:41], s95, v96
	s_and_saveexec_b64 s[44:45], s[40:41]
	s_mov_b32 s1, 0xf149f2ca
	v_mov_b32_e32 v143, s1
	s_or_b64 exec, exec, s[44:45]
	v_cndmask_b32_e32 v144, v207, v144, vcc
	v_cndmask_b32_e64 v145, v207, v145, s[8:9]
	v_cndmask_b32_e64 v146, v207, v146, s[10:11]
	v_cndmask_b32_e64 v147, v207, v147, s[12:13]
	v_cndmask_b32_e64 v148, v207, v148, s[14:15]
	v_cndmask_b32_e64 v149, v207, v149, s[16:17]
	v_cndmask_b32_e64 v150, v207, v150, s[18:19]
	v_cndmask_b32_e64 v151, v207, v151, s[20:21]
	v_cndmask_b32_e64 v152, v207, v152, s[22:23]
	v_cndmask_b32_e64 v153, v207, v153, s[24:25]
	v_cndmask_b32_e64 v154, v207, v154, s[26:27]
	v_cndmask_b32_e64 v155, v207, v155, s[28:29]
	v_cndmask_b32_e64 v156, v207, v156, s[30:31]
	v_cndmask_b32_e64 v157, v207, v157, s[34:35]
	v_cndmask_b32_e64 v158, v207, v158, s[36:37]
	v_cndmask_b32_e64 v159, v207, v159, s[38:39]
